# scan o-reduction: bank-masked DPP adds replace cndmask pairs in the first two transpose-reduce stages (16 fewer VALU per 16 steps)
# speedup vs baseline: 1.0058x; 1.0058x over previous
; __device__ __forceinline__ void scan_unit(const Ctx& C0, const float* scn, int T, int quarter, const float* S0, float* Sout, unsigned char* obase, int mode) {
;     ...
;         for (int k = 0; k < nch; ++k) {
;             const unsigned aq = (unsigned)(size_t)(C.lds + (k & 1) * SLOT_B) + 16u * (unsigned)q, av = (unsigned)(size_t)(C.lds + (k & 1) * SLOT_B) + (320u + (unsigned)irow) * 4u;
;             float osel0, osel1;
;             asm volatile(SCAN_CHUNK_ASM : "+v"(S0x), "+v"(S1x), "+v"(S2x), "+v"(S3x), "=&v"(osel0), "=&v"(osel1) : "v"(aq), "v"(av), "v"(q) : SCAN_CHUNK_CLOBBERS, "memory");
.LBB0_685:
	v_mov_b32 v138, v2
	v_mov_b32 v139, v13
	v_mov_b32 v140, v12
	v_mov_b32 v141, v8
	ds_read_b128 v[164:167], v5 offset:0
	ds_read_b128 v[168:171], v5 offset:256
	ds_read_b128 v[172:175], v5 offset:512
	ds_read_b128 v[176:179], v5 offset:768
	ds_read_b128 v[180:183], v5 offset:1024
	ds_read_b32 v184, v9 offset:0
	ds_read_b128 v[186:189], v5 offset:1536
	ds_read_b128 v[190:193], v5 offset:1792
	ds_read_b128 v[194:197], v5 offset:2048
	ds_read_b128 v[198:201], v5 offset:2304
	ds_read_b128 v[202:205], v5 offset:2560
	ds_read_b32 v206, v9 offset:1536
	s_waitcnt lgkmcnt(0)
	v_pk_mul_f32 v[144:145], v[138:139], v[164:165]
	v_pk_fma_f32 v[144:145], v[140:141], v[166:167], v[144:145]
	v_add_f32 v146, v144, v145
	ds_read_b128 v[208:211], v5 offset:3072
	ds_read_b128 v[212:215], v5 offset:3328
	ds_read_b128 v[216:219], v5 offset:3584
	ds_read_b128 v[220:223], v5 offset:3840
	ds_read_b128 v[224:227], v5 offset:4096
	ds_read_b32 v228, v9 offset:3072
	v_add_f32_dpp v146, v146, v146 quad_perm:[1,0,3,2] row_mask:0xf bank_mask:0xf bound_ctrl:1
	s_nop 0
	s_nop 0
	v_add_f32_dpp v146, v146, v146 quad_perm:[2,3,0,1] row_mask:0xf bank_mask:0xf bound_ctrl:1
	s_nop 0
	v_pk_mul_f32 v[176:177], v[176:177], v[184:185] op_sel_hi:[1,0]
	v_add_f32_dpp v146, v146, v146 row_half_mirror row_mask:0xf bank_mask:0xf bound_ctrl:1
	v_pk_mul_f32 v[178:179], v[178:179], v[184:185] op_sel_hi:[1,0]
	s_waitcnt lgkmcnt(6)
	v_add_f32_dpp v146, v146, v146 row_mirror row_mask:0xf bank_mask:0xf bound_ctrl:1
	v_pk_fma_f32 v[176:177], v[146:147], v[168:169], v[176:177] op_sel_hi:[0,1,1] neg_lo:[1,0,0] neg_hi:[1,0,0]
	v_pk_fma_f32 v[178:179], v[146:147], v[170:171], v[178:179] op_sel_hi:[0,1,1] neg_lo:[1,0,0] neg_hi:[1,0,0]
	v_pk_fma_f32 v[138:139], v[138:139], v[172:173], v[176:177]
	v_pk_fma_f32 v[140:141], v[140:141], v[174:175], v[178:179]
	v_pk_mul_f32 v[144:145], v[138:139], v[186:187]
	v_pk_fma_f32 v[144:145], v[140:141], v[188:189], v[144:145]
	v_add_f32 v146, v144, v145
	ds_read_b128 v[230:233], v5 offset:4608
	ds_read_b128 v[234:237], v5 offset:4864
	ds_read_b128 v[238:241], v5 offset:5120
	ds_read_b128 v[242:245], v5 offset:5376
	ds_read_b128 v[246:249], v5 offset:5632
	ds_read_b32 v250, v9 offset:4608
	v_add_f32_dpp v146, v146, v146 quad_perm:[1,0,3,2] row_mask:0xf bank_mask:0xf bound_ctrl:1
	v_pk_mul_f32 v[180:181], v[138:139], v[180:181]
	v_pk_fma_f32 v[180:181], v[140:141], v[182:183], v[180:181]
	v_add_f32_dpp v146, v146, v146 quad_perm:[2,3,0,1] row_mask:0xf bank_mask:0xf bound_ctrl:1
	v_add_f32 v148, v180, v181
	v_pk_mul_f32 v[198:199], v[198:199], v[206:207] op_sel_hi:[1,0]
	v_add_f32_dpp v146, v146, v146 row_half_mirror row_mask:0xf bank_mask:0xf bound_ctrl:1
	v_pk_mul_f32 v[200:201], v[200:201], v[206:207] op_sel_hi:[1,0]
	s_waitcnt lgkmcnt(6)
	v_add_f32_dpp v146, v146, v146 row_mirror row_mask:0xf bank_mask:0xf bound_ctrl:1
	v_pk_fma_f32 v[198:199], v[146:147], v[190:191], v[198:199] op_sel_hi:[0,1,1] neg_lo:[1,0,0] neg_hi:[1,0,0]
	v_pk_fma_f32 v[200:201], v[146:147], v[192:193], v[200:201] op_sel_hi:[0,1,1] neg_lo:[1,0,0] neg_hi:[1,0,0]
	v_pk_fma_f32 v[138:139], v[138:139], v[194:195], v[198:199]
	v_pk_fma_f32 v[140:141], v[140:141], v[196:197], v[200:201]
	v_pk_mul_f32 v[144:145], v[138:139], v[208:209]
	v_pk_fma_f32 v[144:145], v[140:141], v[210:211], v[144:145]
	v_add_f32 v146, v144, v145
	ds_read_b128 v[164:167], v5 offset:6144
	ds_read_b128 v[168:171], v5 offset:6400
	ds_read_b128 v[172:175], v5 offset:6656
	ds_read_b128 v[176:179], v5 offset:6912
	ds_read_b128 v[180:183], v5 offset:7168
	ds_read_b32 v184, v9 offset:6144
	v_add_f32_dpp v146, v146, v146 quad_perm:[1,0,3,2] row_mask:0xf bank_mask:0xf bound_ctrl:1
	v_pk_mul_f32 v[202:203], v[138:139], v[202:203]
	v_pk_fma_f32 v[202:203], v[140:141], v[204:205], v[202:203]
	v_add_f32_dpp v146, v146, v146 quad_perm:[2,3,0,1] row_mask:0xf bank_mask:0xf bound_ctrl:1
	v_add_f32 v149, v202, v203
	v_pk_mul_f32 v[220:221], v[220:221], v[228:229] op_sel_hi:[1,0]
	v_add_f32_dpp v146, v146, v146 row_half_mirror row_mask:0xf bank_mask:0xf bound_ctrl:1
	v_pk_mul_f32 v[222:223], v[222:223], v[228:229] op_sel_hi:[1,0]
	s_waitcnt lgkmcnt(6)
	v_add_f32_dpp v146, v146, v146 row_mirror row_mask:0xf bank_mask:0xf bound_ctrl:1
	v_pk_fma_f32 v[220:221], v[146:147], v[212:213], v[220:221] op_sel_hi:[0,1,1] neg_lo:[1,0,0] neg_hi:[1,0,0]
	v_pk_fma_f32 v[222:223], v[146:147], v[214:215], v[222:223] op_sel_hi:[0,1,1] neg_lo:[1,0,0] neg_hi:[1,0,0]
	v_pk_fma_f32 v[138:139], v[138:139], v[216:217], v[220:221]
	v_pk_fma_f32 v[140:141], v[140:141], v[218:219], v[222:223]
	v_pk_mul_f32 v[144:145], v[138:139], v[230:231]
	v_pk_fma_f32 v[144:145], v[140:141], v[232:233], v[144:145]
	v_add_f32 v146, v144, v145
	ds_read_b128 v[186:189], v5 offset:7680
	ds_read_b128 v[190:193], v5 offset:7936
	ds_read_b128 v[194:197], v5 offset:8192
	ds_read_b128 v[198:201], v5 offset:8448
	ds_read_b128 v[202:205], v5 offset:8704
	ds_read_b32 v206, v9 offset:7680
	v_add_f32_dpp v146, v146, v146 quad_perm:[1,0,3,2] row_mask:0xf bank_mask:0xf bound_ctrl:1
	v_pk_mul_f32 v[224:225], v[138:139], v[224:225]
	v_pk_fma_f32 v[224:225], v[140:141], v[226:227], v[224:225]
	v_add_f32_dpp v146, v146, v146 quad_perm:[2,3,0,1] row_mask:0xf bank_mask:0xf bound_ctrl:1
	v_add_f32 v150, v224, v225
	v_pk_mul_f32 v[242:243], v[242:243], v[250:251] op_sel_hi:[1,0]
	v_add_f32_dpp v146, v146, v146 row_half_mirror row_mask:0xf bank_mask:0xf bound_ctrl:1
	v_pk_mul_f32 v[244:245], v[244:245], v[250:251] op_sel_hi:[1,0]
	s_waitcnt lgkmcnt(6)
; __device__ __forceinline__ void scan_unit(const Ctx& C0, const float* scn, int T, int quarter, const float* S0, float* Sout, unsigned char* obase, int mode) {
;     ...
;         for (int k = 0; k < nch; ++k) {
;             const unsigned aq = (unsigned)(size_t)(C.lds + (k & 1) * SLOT_B) + 16u * (unsigned)q, av = (unsigned)(size_t)(C.lds + (k & 1) * SLOT_B) + (320u + (unsigned)irow) * 4u;
;             float osel0, osel1;
;             asm volatile(SCAN_CHUNK_ASM : "+v"(S0x), "+v"(S1x), "+v"(S2x), "+v"(S3x), "=&v"(osel0), "=&v"(osel1) : "v"(aq), "v"(av), "v"(q) : SCAN_CHUNK_CLOBBERS, "memory");
	v_add_f32_dpp v146, v146, v146 row_mirror row_mask:0xf bank_mask:0xf bound_ctrl:1
	v_pk_fma_f32 v[242:243], v[146:147], v[234:235], v[242:243] op_sel_hi:[0,1,1] neg_lo:[1,0,0] neg_hi:[1,0,0]
	v_pk_fma_f32 v[244:245], v[146:147], v[236:237], v[244:245] op_sel_hi:[0,1,1] neg_lo:[1,0,0] neg_hi:[1,0,0]
	v_pk_fma_f32 v[138:139], v[138:139], v[238:239], v[242:243]
	v_pk_fma_f32 v[140:141], v[140:141], v[240:241], v[244:245]
	v_pk_mul_f32 v[144:145], v[138:139], v[164:165]
	v_pk_fma_f32 v[144:145], v[140:141], v[166:167], v[144:145]
	v_add_f32 v146, v144, v145
	ds_read_b128 v[208:211], v5 offset:9216
	ds_read_b128 v[212:215], v5 offset:9472
	ds_read_b128 v[216:219], v5 offset:9728
	ds_read_b128 v[220:223], v5 offset:9984
	ds_read_b128 v[224:227], v5 offset:10240
	ds_read_b32 v228, v9 offset:9216
	v_add_f32_dpp v146, v146, v146 quad_perm:[1,0,3,2] row_mask:0xf bank_mask:0xf bound_ctrl:1
	v_pk_mul_f32 v[246:247], v[138:139], v[246:247]
	v_pk_fma_f32 v[246:247], v[140:141], v[248:249], v[246:247]
	v_add_f32_dpp v146, v146, v146 quad_perm:[2,3,0,1] row_mask:0xf bank_mask:0xf bound_ctrl:1
	v_add_f32 v151, v246, v247
	v_pk_mul_f32 v[176:177], v[176:177], v[184:185] op_sel_hi:[1,0]
	v_add_f32_dpp v146, v146, v146 row_half_mirror row_mask:0xf bank_mask:0xf bound_ctrl:1
	v_pk_mul_f32 v[178:179], v[178:179], v[184:185] op_sel_hi:[1,0]
	s_waitcnt lgkmcnt(6)
	v_add_f32_dpp v146, v146, v146 row_mirror row_mask:0xf bank_mask:0xf bound_ctrl:1
	v_pk_fma_f32 v[176:177], v[146:147], v[168:169], v[176:177] op_sel_hi:[0,1,1] neg_lo:[1,0,0] neg_hi:[1,0,0]
	v_pk_fma_f32 v[178:179], v[146:147], v[170:171], v[178:179] op_sel_hi:[0,1,1] neg_lo:[1,0,0] neg_hi:[1,0,0]
	v_pk_fma_f32 v[138:139], v[138:139], v[172:173], v[176:177]
	v_pk_fma_f32 v[140:141], v[140:141], v[174:175], v[178:179]
	v_pk_mul_f32 v[144:145], v[138:139], v[186:187]
	v_pk_fma_f32 v[144:145], v[140:141], v[188:189], v[144:145]
	v_add_f32 v146, v144, v145
	ds_read_b128 v[230:233], v5 offset:10752
	ds_read_b128 v[234:237], v5 offset:11008
	ds_read_b128 v[238:241], v5 offset:11264
	ds_read_b128 v[242:245], v5 offset:11520
	ds_read_b128 v[246:249], v5 offset:11776
	ds_read_b32 v250, v9 offset:10752
	v_add_f32_dpp v146, v146, v146 quad_perm:[1,0,3,2] row_mask:0xf bank_mask:0xf bound_ctrl:1
	v_pk_mul_f32 v[180:181], v[138:139], v[180:181]
	v_pk_fma_f32 v[180:181], v[140:141], v[182:183], v[180:181]
	v_add_f32_dpp v146, v146, v146 quad_perm:[2,3,0,1] row_mask:0xf bank_mask:0xf bound_ctrl:1
	v_add_f32 v152, v180, v181
	v_pk_mul_f32 v[198:199], v[198:199], v[206:207] op_sel_hi:[1,0]
	v_add_f32_dpp v146, v146, v146 row_half_mirror row_mask:0xf bank_mask:0xf bound_ctrl:1
	v_pk_mul_f32 v[200:201], v[200:201], v[206:207] op_sel_hi:[1,0]
	s_waitcnt lgkmcnt(6)
	v_add_f32_dpp v146, v146, v146 row_mirror row_mask:0xf bank_mask:0xf bound_ctrl:1
	v_pk_fma_f32 v[198:199], v[146:147], v[190:191], v[198:199] op_sel_hi:[0,1,1] neg_lo:[1,0,0] neg_hi:[1,0,0]
	v_pk_fma_f32 v[200:201], v[146:147], v[192:193], v[200:201] op_sel_hi:[0,1,1] neg_lo:[1,0,0] neg_hi:[1,0,0]
	v_pk_fma_f32 v[138:139], v[138:139], v[194:195], v[198:199]
	v_pk_fma_f32 v[140:141], v[140:141], v[196:197], v[200:201]
	v_pk_mul_f32 v[144:145], v[138:139], v[208:209]
	v_pk_fma_f32 v[144:145], v[140:141], v[210:211], v[144:145]
	v_add_f32 v146, v144, v145
	ds_read_b128 v[164:167], v5 offset:12288
	ds_read_b128 v[168:171], v5 offset:12544
	ds_read_b128 v[172:175], v5 offset:12800
	ds_read_b128 v[176:179], v5 offset:13056
	ds_read_b128 v[180:183], v5 offset:13312
	ds_read_b32 v184, v9 offset:12288
	v_add_f32_dpp v146, v146, v146 quad_perm:[1,0,3,2] row_mask:0xf bank_mask:0xf bound_ctrl:1
	v_pk_mul_f32 v[202:203], v[138:139], v[202:203]
	v_pk_fma_f32 v[202:203], v[140:141], v[204:205], v[202:203]
	v_add_f32_dpp v146, v146, v146 quad_perm:[2,3,0,1] row_mask:0xf bank_mask:0xf bound_ctrl:1
	v_add_f32 v153, v202, v203
	v_pk_mul_f32 v[220:221], v[220:221], v[228:229] op_sel_hi:[1,0]
	v_add_f32_dpp v146, v146, v146 row_half_mirror row_mask:0xf bank_mask:0xf bound_ctrl:1
	v_pk_mul_f32 v[222:223], v[222:223], v[228:229] op_sel_hi:[1,0]
	s_waitcnt lgkmcnt(6)
	v_add_f32_dpp v146, v146, v146 row_mirror row_mask:0xf bank_mask:0xf bound_ctrl:1
	v_pk_fma_f32 v[220:221], v[146:147], v[212:213], v[220:221] op_sel_hi:[0,1,1] neg_lo:[1,0,0] neg_hi:[1,0,0]
	v_pk_fma_f32 v[222:223], v[146:147], v[214:215], v[222:223] op_sel_hi:[0,1,1] neg_lo:[1,0,0] neg_hi:[1,0,0]
	v_pk_fma_f32 v[138:139], v[138:139], v[216:217], v[220:221]
	v_pk_fma_f32 v[140:141], v[140:141], v[218:219], v[222:223]
	v_pk_mul_f32 v[144:145], v[138:139], v[230:231]
	v_pk_fma_f32 v[144:145], v[140:141], v[232:233], v[144:145]
	v_add_f32 v146, v144, v145
	ds_read_b128 v[186:189], v5 offset:13824
	ds_read_b128 v[190:193], v5 offset:14080
	ds_read_b128 v[194:197], v5 offset:14336
	ds_read_b128 v[198:201], v5 offset:14592
	ds_read_b128 v[202:205], v5 offset:14848
	ds_read_b32 v206, v9 offset:13824
	v_add_f32_dpp v146, v146, v146 quad_perm:[1,0,3,2] row_mask:0xf bank_mask:0xf bound_ctrl:1
	v_pk_mul_f32 v[224:225], v[138:139], v[224:225]
	v_pk_fma_f32 v[224:225], v[140:141], v[226:227], v[224:225]
	v_add_f32_dpp v146, v146, v146 quad_perm:[2,3,0,1] row_mask:0xf bank_mask:0xf bound_ctrl:1
	v_add_f32 v154, v224, v225
	v_pk_mul_f32 v[242:243], v[242:243], v[250:251] op_sel_hi:[1,0]
	v_add_f32_dpp v146, v146, v146 row_half_mirror row_mask:0xf bank_mask:0xf bound_ctrl:1
	v_pk_mul_f32 v[244:245], v[244:245], v[250:251] op_sel_hi:[1,0]
	s_waitcnt lgkmcnt(6)
	v_add_f32_dpp v146, v146, v146 row_mirror row_mask:0xf bank_mask:0xf bound_ctrl:1
	v_pk_fma_f32 v[242:243], v[146:147], v[234:235], v[242:243] op_sel_hi:[0,1,1] neg_lo:[1,0,0] neg_hi:[1,0,0]
	v_pk_fma_f32 v[244:245], v[146:147], v[236:237], v[244:245] op_sel_hi:[0,1,1] neg_lo:[1,0,0] neg_hi:[1,0,0]
	v_pk_fma_f32 v[138:139], v[138:139], v[238:239], v[242:243]
	v_pk_fma_f32 v[140:141], v[140:141], v[240:241], v[244:245]
	v_pk_mul_f32 v[144:145], v[138:139], v[164:165]
	v_pk_fma_f32 v[144:145], v[140:141], v[166:167], v[144:145]
	v_add_f32 v146, v144, v145
	ds_read_b128 v[208:211], v5 offset:15360
	ds_read_b128 v[212:215], v5 offset:15616
	ds_read_b128 v[216:219], v5 offset:15872
	ds_read_b128 v[220:223], v5 offset:16128
	ds_read_b128 v[224:227], v5 offset:16384
	ds_read_b32 v228, v9 offset:15360
	v_add_f32_dpp v146, v146, v146 quad_perm:[1,0,3,2] row_mask:0xf bank_mask:0xf bound_ctrl:1
	v_pk_mul_f32 v[246:247], v[138:139], v[246:247]
	v_pk_fma_f32 v[246:247], v[140:141], v[248:249], v[246:247]
	v_add_f32_dpp v146, v146, v146 quad_perm:[2,3,0,1] row_mask:0xf bank_mask:0xf bound_ctrl:1
	v_add_f32 v155, v246, v247
	v_pk_mul_f32 v[176:177], v[176:177], v[184:185] op_sel_hi:[1,0]
	v_add_f32_dpp v146, v146, v146 row_half_mirror row_mask:0xf bank_mask:0xf bound_ctrl:1
	v_pk_mul_f32 v[178:179], v[178:179], v[184:185] op_sel_hi:[1,0]
	s_waitcnt lgkmcnt(6)
	v_add_f32_dpp v146, v146, v146 row_mirror row_mask:0xf bank_mask:0xf bound_ctrl:1
	v_pk_fma_f32 v[176:177], v[146:147], v[168:169], v[176:177] op_sel_hi:[0,1,1] neg_lo:[1,0,0] neg_hi:[1,0,0]
	v_pk_fma_f32 v[178:179], v[146:147], v[170:171], v[178:179] op_sel_hi:[0,1,1] neg_lo:[1,0,0] neg_hi:[1,0,0]
	v_pk_fma_f32 v[138:139], v[138:139], v[172:173], v[176:177]
	v_pk_fma_f32 v[140:141], v[140:141], v[174:175], v[178:179]
	v_pk_mul_f32 v[144:145], v[138:139], v[186:187]
	v_pk_fma_f32 v[144:145], v[140:141], v[188:189], v[144:145]
	v_add_f32 v146, v144, v145
	ds_read_b128 v[230:233], v5 offset:16896
	ds_read_b128 v[234:237], v5 offset:17152
	ds_read_b128 v[238:241], v5 offset:17408
	ds_read_b128 v[242:245], v5 offset:17664
	ds_read_b128 v[246:249], v5 offset:17920
	ds_read_b32 v250, v9 offset:16896
	v_add_f32_dpp v146, v146, v146 quad_perm:[1,0,3,2] row_mask:0xf bank_mask:0xf bound_ctrl:1
	v_pk_mul_f32 v[180:181], v[138:139], v[180:181]
	v_pk_fma_f32 v[180:181], v[140:141], v[182:183], v[180:181]
	v_add_f32_dpp v146, v146, v146 quad_perm:[2,3,0,1] row_mask:0xf bank_mask:0xf bound_ctrl:1
	v_add_f32 v156, v180, v181
	v_pk_mul_f32 v[198:199], v[198:199], v[206:207] op_sel_hi:[1,0]
	v_add_f32_dpp v146, v146, v146 row_half_mirror row_mask:0xf bank_mask:0xf bound_ctrl:1
	v_pk_mul_f32 v[200:201], v[200:201], v[206:207] op_sel_hi:[1,0]
	s_waitcnt lgkmcnt(6)
	v_add_f32_dpp v146, v146, v146 row_mirror row_mask:0xf bank_mask:0xf bound_ctrl:1
	v_pk_fma_f32 v[198:199], v[146:147], v[190:191], v[198:199] op_sel_hi:[0,1,1] neg_lo:[1,0,0] neg_hi:[1,0,0]
	v_pk_fma_f32 v[200:201], v[146:147], v[192:193], v[200:201] op_sel_hi:[0,1,1] neg_lo:[1,0,0] neg_hi:[1,0,0]
	v_pk_fma_f32 v[138:139], v[138:139], v[194:195], v[198:199]
	v_pk_fma_f32 v[140:141], v[140:141], v[196:197], v[200:201]
	v_pk_mul_f32 v[144:145], v[138:139], v[208:209]
	v_pk_fma_f32 v[144:145], v[140:141], v[210:211], v[144:145]
	v_add_f32 v146, v144, v145
	ds_read_b128 v[164:167], v5 offset:18432
	ds_read_b128 v[168:171], v5 offset:18688
	ds_read_b128 v[172:175], v5 offset:18944
	ds_read_b128 v[176:179], v5 offset:19200
	ds_read_b128 v[180:183], v5 offset:19456
	ds_read_b32 v184, v9 offset:18432
	v_add_f32_dpp v146, v146, v146 quad_perm:[1,0,3,2] row_mask:0xf bank_mask:0xf bound_ctrl:1
	v_pk_mul_f32 v[202:203], v[138:139], v[202:203]
	v_pk_fma_f32 v[202:203], v[140:141], v[204:205], v[202:203]
	v_add_f32_dpp v146, v146, v146 quad_perm:[2,3,0,1] row_mask:0xf bank_mask:0xf bound_ctrl:1
	v_add_f32 v157, v202, v203
	v_pk_mul_f32 v[220:221], v[220:221], v[228:229] op_sel_hi:[1,0]
	v_add_f32_dpp v146, v146, v146 row_half_mirror row_mask:0xf bank_mask:0xf bound_ctrl:1
	v_pk_mul_f32 v[222:223], v[222:223], v[228:229] op_sel_hi:[1,0]
	s_waitcnt lgkmcnt(6)
	v_add_f32_dpp v146, v146, v146 row_mirror row_mask:0xf bank_mask:0xf bound_ctrl:1
	v_pk_fma_f32 v[220:221], v[146:147], v[212:213], v[220:221] op_sel_hi:[0,1,1] neg_lo:[1,0,0] neg_hi:[1,0,0]
	v_pk_fma_f32 v[222:223], v[146:147], v[214:215], v[222:223] op_sel_hi:[0,1,1] neg_lo:[1,0,0] neg_hi:[1,0,0]
	v_pk_fma_f32 v[138:139], v[138:139], v[216:217], v[220:221]
	v_pk_fma_f32 v[140:141], v[140:141], v[218:219], v[222:223]
	v_pk_mul_f32 v[144:145], v[138:139], v[230:231]
	v_pk_fma_f32 v[144:145], v[140:141], v[232:233], v[144:145]
	v_add_f32 v146, v144, v145
	ds_read_b128 v[186:189], v5 offset:19968
	ds_read_b128 v[190:193], v5 offset:20224
	ds_read_b128 v[194:197], v5 offset:20480
	ds_read_b128 v[198:201], v5 offset:20736
	ds_read_b128 v[202:205], v5 offset:20992
	ds_read_b32 v206, v9 offset:19968
	v_add_f32_dpp v146, v146, v146 quad_perm:[1,0,3,2] row_mask:0xf bank_mask:0xf bound_ctrl:1
	v_pk_mul_f32 v[224:225], v[138:139], v[224:225]
	v_pk_fma_f32 v[224:225], v[140:141], v[226:227], v[224:225]
	v_add_f32_dpp v146, v146, v146 quad_perm:[2,3,0,1] row_mask:0xf bank_mask:0xf bound_ctrl:1
	v_add_f32 v158, v224, v225
	v_pk_mul_f32 v[242:243], v[242:243], v[250:251] op_sel_hi:[1,0]
	v_add_f32_dpp v146, v146, v146 row_half_mirror row_mask:0xf bank_mask:0xf bound_ctrl:1
	v_pk_mul_f32 v[244:245], v[244:245], v[250:251] op_sel_hi:[1,0]
	s_waitcnt lgkmcnt(6)
	v_add_f32_dpp v146, v146, v146 row_mirror row_mask:0xf bank_mask:0xf bound_ctrl:1
	v_pk_fma_f32 v[242:243], v[146:147], v[234:235], v[242:243] op_sel_hi:[0,1,1] neg_lo:[1,0,0] neg_hi:[1,0,0]
	v_pk_fma_f32 v[244:245], v[146:147], v[236:237], v[244:245] op_sel_hi:[0,1,1] neg_lo:[1,0,0] neg_hi:[1,0,0]
	v_pk_fma_f32 v[138:139], v[138:139], v[238:239], v[242:243]
	v_pk_fma_f32 v[140:141], v[140:141], v[240:241], v[244:245]
	v_pk_mul_f32 v[144:145], v[138:139], v[164:165]
	v_pk_fma_f32 v[144:145], v[140:141], v[166:167], v[144:145]
	v_add_f32 v146, v144, v145
	ds_read_b128 v[208:211], v5 offset:21504
	ds_read_b128 v[212:215], v5 offset:21760
	ds_read_b128 v[216:219], v5 offset:22016
	ds_read_b128 v[220:223], v5 offset:22272
	ds_read_b128 v[224:227], v5 offset:22528
	ds_read_b32 v228, v9 offset:21504
	v_add_f32_dpp v146, v146, v146 quad_perm:[1,0,3,2] row_mask:0xf bank_mask:0xf bound_ctrl:1
	v_pk_mul_f32 v[246:247], v[138:139], v[246:247]
	v_pk_fma_f32 v[246:247], v[140:141], v[248:249], v[246:247]
	v_add_f32_dpp v146, v146, v146 quad_perm:[2,3,0,1] row_mask:0xf bank_mask:0xf bound_ctrl:1
	v_add_f32 v159, v246, v247
	v_pk_mul_f32 v[176:177], v[176:177], v[184:185] op_sel_hi:[1,0]
	v_add_f32_dpp v146, v146, v146 row_half_mirror row_mask:0xf bank_mask:0xf bound_ctrl:1
	v_pk_mul_f32 v[178:179], v[178:179], v[184:185] op_sel_hi:[1,0]
	s_waitcnt lgkmcnt(6)
	v_add_f32_dpp v146, v146, v146 row_mirror row_mask:0xf bank_mask:0xf bound_ctrl:1
	v_pk_fma_f32 v[176:177], v[146:147], v[168:169], v[176:177] op_sel_hi:[0,1,1] neg_lo:[1,0,0] neg_hi:[1,0,0]
	v_pk_fma_f32 v[178:179], v[146:147], v[170:171], v[178:179] op_sel_hi:[0,1,1] neg_lo:[1,0,0] neg_hi:[1,0,0]
	v_pk_fma_f32 v[138:139], v[138:139], v[172:173], v[176:177]
	v_pk_fma_f32 v[140:141], v[140:141], v[174:175], v[178:179]
	v_pk_mul_f32 v[144:145], v[138:139], v[186:187]
	v_pk_fma_f32 v[144:145], v[140:141], v[188:189], v[144:145]
	v_add_f32 v146, v144, v145
	ds_read_b128 v[230:233], v5 offset:23040
	ds_read_b128 v[234:237], v5 offset:23296
	ds_read_b128 v[238:241], v5 offset:23552
	ds_read_b128 v[242:245], v5 offset:23808
	ds_read_b128 v[246:249], v5 offset:24064
	ds_read_b32 v250, v9 offset:23040
	v_add_f32_dpp v146, v146, v146 quad_perm:[1,0,3,2] row_mask:0xf bank_mask:0xf bound_ctrl:1
	v_pk_mul_f32 v[180:181], v[138:139], v[180:181]
	v_pk_fma_f32 v[180:181], v[140:141], v[182:183], v[180:181]
	v_add_f32_dpp v146, v146, v146 quad_perm:[2,3,0,1] row_mask:0xf bank_mask:0xf bound_ctrl:1
	v_add_f32 v160, v180, v181
	v_pk_mul_f32 v[198:199], v[198:199], v[206:207] op_sel_hi:[1,0]
	v_add_f32_dpp v146, v146, v146 row_half_mirror row_mask:0xf bank_mask:0xf bound_ctrl:1
	v_pk_mul_f32 v[200:201], v[200:201], v[206:207] op_sel_hi:[1,0]
	s_waitcnt lgkmcnt(6)
	v_add_f32_dpp v146, v146, v146 row_mirror row_mask:0xf bank_mask:0xf bound_ctrl:1
	v_pk_fma_f32 v[198:199], v[146:147], v[190:191], v[198:199] op_sel_hi:[0,1,1] neg_lo:[1,0,0] neg_hi:[1,0,0]
	v_pk_fma_f32 v[200:201], v[146:147], v[192:193], v[200:201] op_sel_hi:[0,1,1] neg_lo:[1,0,0] neg_hi:[1,0,0]
	v_pk_fma_f32 v[138:139], v[138:139], v[194:195], v[198:199]
	v_pk_fma_f32 v[140:141], v[140:141], v[196:197], v[200:201]
	v_pk_mul_f32 v[144:145], v[138:139], v[208:209]
	v_pk_fma_f32 v[144:145], v[140:141], v[210:211], v[144:145]
	v_add_f32 v146, v144, v145
	ds_read_b128 v[164:167], v5 offset:24576
	ds_read_b128 v[168:171], v5 offset:24832
	ds_read_b128 v[172:175], v5 offset:25088
	ds_read_b128 v[176:179], v5 offset:25344
	ds_read_b128 v[180:183], v5 offset:25600
	ds_read_b32 v184, v9 offset:24576
	v_add_f32_dpp v146, v146, v146 quad_perm:[1,0,3,2] row_mask:0xf bank_mask:0xf bound_ctrl:1
	v_pk_mul_f32 v[202:203], v[138:139], v[202:203]
	v_pk_fma_f32 v[202:203], v[140:141], v[204:205], v[202:203]
	v_add_f32_dpp v146, v146, v146 quad_perm:[2,3,0,1] row_mask:0xf bank_mask:0xf bound_ctrl:1
	v_add_f32 v161, v202, v203
	v_pk_mul_f32 v[220:221], v[220:221], v[228:229] op_sel_hi:[1,0]
	v_add_f32_dpp v146, v146, v146 row_half_mirror row_mask:0xf bank_mask:0xf bound_ctrl:1
	v_pk_mul_f32 v[222:223], v[222:223], v[228:229] op_sel_hi:[1,0]
	s_waitcnt lgkmcnt(6)
	v_add_f32_dpp v146, v146, v146 row_mirror row_mask:0xf bank_mask:0xf bound_ctrl:1
	v_pk_fma_f32 v[220:221], v[146:147], v[212:213], v[220:221] op_sel_hi:[0,1,1] neg_lo:[1,0,0] neg_hi:[1,0,0]
	v_pk_fma_f32 v[222:223], v[146:147], v[214:215], v[222:223] op_sel_hi:[0,1,1] neg_lo:[1,0,0] neg_hi:[1,0,0]
	v_pk_fma_f32 v[138:139], v[138:139], v[216:217], v[220:221]
	v_pk_fma_f32 v[140:141], v[140:141], v[218:219], v[222:223]
	v_pk_mul_f32 v[144:145], v[138:139], v[230:231]
	v_pk_fma_f32 v[144:145], v[140:141], v[232:233], v[144:145]
	v_add_f32 v146, v144, v145
	ds_read_b128 v[186:189], v5 offset:26112
	ds_read_b128 v[190:193], v5 offset:26368
	ds_read_b128 v[194:197], v5 offset:26624
	ds_read_b128 v[198:201], v5 offset:26880
	ds_read_b128 v[202:205], v5 offset:27136
	ds_read_b32 v206, v9 offset:26112
	v_add_f32_dpp v146, v146, v146 quad_perm:[1,0,3,2] row_mask:0xf bank_mask:0xf bound_ctrl:1
	v_pk_mul_f32 v[224:225], v[138:139], v[224:225]
	v_pk_fma_f32 v[224:225], v[140:141], v[226:227], v[224:225]
	v_add_f32_dpp v146, v146, v146 quad_perm:[2,3,0,1] row_mask:0xf bank_mask:0xf bound_ctrl:1
	v_add_f32 v162, v224, v225
	v_pk_mul_f32 v[242:243], v[242:243], v[250:251] op_sel_hi:[1,0]
	v_add_f32_dpp v146, v146, v146 row_half_mirror row_mask:0xf bank_mask:0xf bound_ctrl:1
	v_pk_mul_f32 v[244:245], v[244:245], v[250:251] op_sel_hi:[1,0]
	s_waitcnt lgkmcnt(6)
	v_add_f32_dpp v146, v146, v146 row_mirror row_mask:0xf bank_mask:0xf bound_ctrl:1
	v_pk_fma_f32 v[242:243], v[146:147], v[234:235], v[242:243] op_sel_hi:[0,1,1] neg_lo:[1,0,0] neg_hi:[1,0,0]
	v_pk_fma_f32 v[244:245], v[146:147], v[236:237], v[244:245] op_sel_hi:[0,1,1] neg_lo:[1,0,0] neg_hi:[1,0,0]
	v_pk_fma_f32 v[138:139], v[138:139], v[238:239], v[242:243]
	v_pk_fma_f32 v[140:141], v[140:141], v[240:241], v[244:245]
	v_pk_mul_f32 v[144:145], v[138:139], v[164:165]
	v_pk_fma_f32 v[144:145], v[140:141], v[166:167], v[144:145]
	v_add_f32 v146, v144, v145
	ds_read_b128 v[208:211], v5 offset:27648
	ds_read_b128 v[212:215], v5 offset:27904
	ds_read_b128 v[216:219], v5 offset:28160
	ds_read_b128 v[220:223], v5 offset:28416
	ds_read_b128 v[224:227], v5 offset:28672
	ds_read_b32 v228, v9 offset:27648
	v_add_f32_dpp v146, v146, v146 quad_perm:[1,0,3,2] row_mask:0xf bank_mask:0xf bound_ctrl:1
	v_pk_mul_f32 v[246:247], v[138:139], v[246:247]
	v_pk_fma_f32 v[246:247], v[140:141], v[248:249], v[246:247]
	v_add_f32_dpp v146, v146, v146 quad_perm:[2,3,0,1] row_mask:0xf bank_mask:0xf bound_ctrl:1
	v_add_f32 v163, v246, v247
	v_pk_mul_f32 v[176:177], v[176:177], v[184:185] op_sel_hi:[1,0]
	v_add_f32_dpp v146, v146, v146 row_half_mirror row_mask:0xf bank_mask:0xf bound_ctrl:1
	v_pk_mul_f32 v[178:179], v[178:179], v[184:185] op_sel_hi:[1,0]
	s_waitcnt lgkmcnt(6)
	v_add_f32_dpp v146, v146, v146 row_mirror row_mask:0xf bank_mask:0xf bound_ctrl:1
	v_pk_fma_f32 v[176:177], v[146:147], v[168:169], v[176:177] op_sel_hi:[0,1,1] neg_lo:[1,0,0] neg_hi:[1,0,0]
	v_pk_fma_f32 v[178:179], v[146:147], v[170:171], v[178:179] op_sel_hi:[0,1,1] neg_lo:[1,0,0] neg_hi:[1,0,0]
	v_pk_fma_f32 v[138:139], v[138:139], v[172:173], v[176:177]
	v_pk_fma_f32 v[140:141], v[140:141], v[174:175], v[178:179]
	v_pk_mul_f32 v[144:145], v[138:139], v[186:187]
	v_pk_fma_f32 v[144:145], v[140:141], v[188:189], v[144:145]
	v_add_f32 v146, v144, v145
	v_add_f32_dpp v230, v148, v148 row_mirror row_mask:0xf bank_mask:0x3 bound_ctrl:1
	v_add_f32_dpp v230, v156, v156 row_mirror row_mask:0xf bank_mask:0xc bound_ctrl:1
	v_add_f32_dpp v231, v149, v149 row_mirror row_mask:0xf bank_mask:0x3 bound_ctrl:1
	v_add_f32_dpp v231, v157, v157 row_mirror row_mask:0xf bank_mask:0xc bound_ctrl:1
	v_add_f32_dpp v232, v150, v150 row_mirror row_mask:0xf bank_mask:0x3 bound_ctrl:1
	v_add_f32_dpp v232, v158, v158 row_mirror row_mask:0xf bank_mask:0xc bound_ctrl:1
	v_add_f32_dpp v233, v151, v151 row_mirror row_mask:0xf bank_mask:0x3 bound_ctrl:1
	v_add_f32_dpp v233, v159, v159 row_mirror row_mask:0xf bank_mask:0xc bound_ctrl:1
	v_add_f32_dpp v234, v152, v152 row_mirror row_mask:0xf bank_mask:0x3 bound_ctrl:1
	v_add_f32_dpp v234, v160, v160 row_mirror row_mask:0xf bank_mask:0xc bound_ctrl:1
	v_add_f32_dpp v235, v153, v153 row_mirror row_mask:0xf bank_mask:0x3 bound_ctrl:1
	v_add_f32_dpp v235, v161, v161 row_mirror row_mask:0xf bank_mask:0xc bound_ctrl:1
	v_add_f32_dpp v236, v154, v154 row_mirror row_mask:0xf bank_mask:0x3 bound_ctrl:1
	v_add_f32_dpp v236, v162, v162 row_mirror row_mask:0xf bank_mask:0xc bound_ctrl:1
	v_add_f32_dpp v237, v155, v155 row_mirror row_mask:0xf bank_mask:0x3 bound_ctrl:1
	v_add_f32_dpp v237, v163, v163 row_mirror row_mask:0xf bank_mask:0xc bound_ctrl:1
	v_add_f32_dpp v238, v230, v230 row_half_mirror row_mask:0xf bank_mask:0x5 bound_ctrl:1
	v_add_f32_dpp v238, v234, v234 row_half_mirror row_mask:0xf bank_mask:0xa bound_ctrl:1
	v_add_f32_dpp v239, v231, v231 row_half_mirror row_mask:0xf bank_mask:0x5 bound_ctrl:1
	v_add_f32_dpp v239, v235, v235 row_half_mirror row_mask:0xf bank_mask:0xa bound_ctrl:1
	v_add_f32_dpp v240, v232, v232 row_half_mirror row_mask:0xf bank_mask:0x5 bound_ctrl:1
	v_add_f32_dpp v240, v236, v236 row_half_mirror row_mask:0xf bank_mask:0xa bound_ctrl:1
	v_add_f32_dpp v241, v233, v233 row_half_mirror row_mask:0xf bank_mask:0x5 bound_ctrl:1
	v_add_f32_dpp v241, v237, v237 row_half_mirror row_mask:0xf bank_mask:0xa bound_ctrl:1
	v_and_b32 v244, 2, v3
	v_cmp_ne_u32 vcc, 0, v244
	v_cndmask_b32 v244, v240, v238, vcc
	v_cndmask_b32 v245, v241, v239, vcc
	v_cndmask_b32 v242, v238, v240, vcc
	v_cndmask_b32 v243, v239, v241, vcc
	v_add_f32_dpp v242, v244, v242 quad_perm:[2,3,0,1] row_mask:0xf bank_mask:0xf bound_ctrl:1
	v_add_f32_dpp v243, v245, v243 quad_perm:[2,3,0,1] row_mask:0xf bank_mask:0xf bound_ctrl:1
	v_and_b32 v244, 1, v3
	v_cmp_ne_u32 vcc, 0, v244
	v_cndmask_b32 v244, v243, v242, vcc
	v_cndmask_b32 v245, v242, v243, vcc
	s_nop 0
	v_add_f32_dpp v18, v244, v245 quad_perm:[1,0,3,2] row_mask:0xf bank_mask:0xf bound_ctrl:1
	ds_read_b128 v[230:233], v5 offset:29184
	ds_read_b128 v[234:237], v5 offset:29440
	ds_read_b128 v[238:241], v5 offset:29696
	ds_read_b128 v[242:245], v5 offset:29952
	ds_read_b128 v[246:249], v5 offset:30208
	ds_read_b32 v250, v9 offset:29184
	v_add_f32_dpp v146, v146, v146 quad_perm:[1,0,3,2] row_mask:0xf bank_mask:0xf bound_ctrl:1
	v_pk_mul_f32 v[180:181], v[138:139], v[180:181]
	v_pk_fma_f32 v[180:181], v[140:141], v[182:183], v[180:181]
	v_add_f32_dpp v146, v146, v146 quad_perm:[2,3,0,1] row_mask:0xf bank_mask:0xf bound_ctrl:1
	v_add_f32 v148, v180, v181
	v_pk_mul_f32 v[198:199], v[198:199], v[206:207] op_sel_hi:[1,0]
	v_add_f32_dpp v146, v146, v146 row_half_mirror row_mask:0xf bank_mask:0xf bound_ctrl:1
	v_pk_mul_f32 v[200:201], v[200:201], v[206:207] op_sel_hi:[1,0]
	s_waitcnt lgkmcnt(6)
	v_add_f32_dpp v146, v146, v146 row_mirror row_mask:0xf bank_mask:0xf bound_ctrl:1
	v_pk_fma_f32 v[198:199], v[146:147], v[190:191], v[198:199] op_sel_hi:[0,1,1] neg_lo:[1,0,0] neg_hi:[1,0,0]
	v_pk_fma_f32 v[200:201], v[146:147], v[192:193], v[200:201] op_sel_hi:[0,1,1] neg_lo:[1,0,0] neg_hi:[1,0,0]
	v_pk_fma_f32 v[138:139], v[138:139], v[194:195], v[198:199]
	v_pk_fma_f32 v[140:141], v[140:141], v[196:197], v[200:201]
	v_pk_mul_f32 v[144:145], v[138:139], v[208:209]
	v_pk_fma_f32 v[144:145], v[140:141], v[210:211], v[144:145]
	v_add_f32 v146, v144, v145
	ds_read_b128 v[164:167], v5 offset:30720
	ds_read_b128 v[168:171], v5 offset:30976
	ds_read_b128 v[172:175], v5 offset:31232
	ds_read_b128 v[176:179], v5 offset:31488
	ds_read_b128 v[180:183], v5 offset:31744
	ds_read_b32 v184, v9 offset:30720
	v_add_f32_dpp v146, v146, v146 quad_perm:[1,0,3,2] row_mask:0xf bank_mask:0xf bound_ctrl:1
	v_pk_mul_f32 v[202:203], v[138:139], v[202:203]
	v_pk_fma_f32 v[202:203], v[140:141], v[204:205], v[202:203]
	v_add_f32_dpp v146, v146, v146 quad_perm:[2,3,0,1] row_mask:0xf bank_mask:0xf bound_ctrl:1
	v_add_f32 v149, v202, v203
	v_pk_mul_f32 v[220:221], v[220:221], v[228:229] op_sel_hi:[1,0]
	v_add_f32_dpp v146, v146, v146 row_half_mirror row_mask:0xf bank_mask:0xf bound_ctrl:1
	v_pk_mul_f32 v[222:223], v[222:223], v[228:229] op_sel_hi:[1,0]
	s_waitcnt lgkmcnt(6)
	v_add_f32_dpp v146, v146, v146 row_mirror row_mask:0xf bank_mask:0xf bound_ctrl:1
	v_pk_fma_f32 v[220:221], v[146:147], v[212:213], v[220:221] op_sel_hi:[0,1,1] neg_lo:[1,0,0] neg_hi:[1,0,0]
	v_pk_fma_f32 v[222:223], v[146:147], v[214:215], v[222:223] op_sel_hi:[0,1,1] neg_lo:[1,0,0] neg_hi:[1,0,0]
	v_pk_fma_f32 v[138:139], v[138:139], v[216:217], v[220:221]
	v_pk_fma_f32 v[140:141], v[140:141], v[218:219], v[222:223]
	v_pk_mul_f32 v[144:145], v[138:139], v[230:231]
	v_pk_fma_f32 v[144:145], v[140:141], v[232:233], v[144:145]
	v_add_f32 v146, v144, v145
	ds_read_b128 v[186:189], v5 offset:32256
	ds_read_b128 v[190:193], v5 offset:32512
	ds_read_b128 v[194:197], v5 offset:32768
	ds_read_b128 v[198:201], v5 offset:33024
	ds_read_b128 v[202:205], v5 offset:33280
	ds_read_b32 v206, v9 offset:32256
	v_add_f32_dpp v146, v146, v146 quad_perm:[1,0,3,2] row_mask:0xf bank_mask:0xf bound_ctrl:1
	v_pk_mul_f32 v[224:225], v[138:139], v[224:225]
	v_pk_fma_f32 v[224:225], v[140:141], v[226:227], v[224:225]
	v_add_f32_dpp v146, v146, v146 quad_perm:[2,3,0,1] row_mask:0xf bank_mask:0xf bound_ctrl:1
	v_add_f32 v150, v224, v225
	v_pk_mul_f32 v[242:243], v[242:243], v[250:251] op_sel_hi:[1,0]
	v_add_f32_dpp v146, v146, v146 row_half_mirror row_mask:0xf bank_mask:0xf bound_ctrl:1
	v_pk_mul_f32 v[244:245], v[244:245], v[250:251] op_sel_hi:[1,0]
	s_waitcnt lgkmcnt(6)
	v_add_f32_dpp v146, v146, v146 row_mirror row_mask:0xf bank_mask:0xf bound_ctrl:1
	v_pk_fma_f32 v[242:243], v[146:147], v[234:235], v[242:243] op_sel_hi:[0,1,1] neg_lo:[1,0,0] neg_hi:[1,0,0]
	v_pk_fma_f32 v[244:245], v[146:147], v[236:237], v[244:245] op_sel_hi:[0,1,1] neg_lo:[1,0,0] neg_hi:[1,0,0]
	v_pk_fma_f32 v[138:139], v[138:139], v[238:239], v[242:243]
	v_pk_fma_f32 v[140:141], v[140:141], v[240:241], v[244:245]
	v_pk_mul_f32 v[144:145], v[138:139], v[164:165]
	v_pk_fma_f32 v[144:145], v[140:141], v[166:167], v[144:145]
	v_add_f32 v146, v144, v145
	ds_read_b128 v[208:211], v5 offset:33792
	ds_read_b128 v[212:215], v5 offset:34048
	ds_read_b128 v[216:219], v5 offset:34304
	ds_read_b128 v[220:223], v5 offset:34560
	ds_read_b128 v[224:227], v5 offset:34816
	ds_read_b32 v228, v9 offset:33792
	v_add_f32_dpp v146, v146, v146 quad_perm:[1,0,3,2] row_mask:0xf bank_mask:0xf bound_ctrl:1
	v_pk_mul_f32 v[246:247], v[138:139], v[246:247]
	v_pk_fma_f32 v[246:247], v[140:141], v[248:249], v[246:247]
	v_add_f32_dpp v146, v146, v146 quad_perm:[2,3,0,1] row_mask:0xf bank_mask:0xf bound_ctrl:1
	v_add_f32 v151, v246, v247
	v_pk_mul_f32 v[176:177], v[176:177], v[184:185] op_sel_hi:[1,0]
	v_add_f32_dpp v146, v146, v146 row_half_mirror row_mask:0xf bank_mask:0xf bound_ctrl:1
	v_pk_mul_f32 v[178:179], v[178:179], v[184:185] op_sel_hi:[1,0]
	s_waitcnt lgkmcnt(6)
	v_add_f32_dpp v146, v146, v146 row_mirror row_mask:0xf bank_mask:0xf bound_ctrl:1
	v_pk_fma_f32 v[176:177], v[146:147], v[168:169], v[176:177] op_sel_hi:[0,1,1] neg_lo:[1,0,0] neg_hi:[1,0,0]
	v_pk_fma_f32 v[178:179], v[146:147], v[170:171], v[178:179] op_sel_hi:[0,1,1] neg_lo:[1,0,0] neg_hi:[1,0,0]
	v_pk_fma_f32 v[138:139], v[138:139], v[172:173], v[176:177]
	v_pk_fma_f32 v[140:141], v[140:141], v[174:175], v[178:179]
	v_pk_mul_f32 v[144:145], v[138:139], v[186:187]
	v_pk_fma_f32 v[144:145], v[140:141], v[188:189], v[144:145]
	v_add_f32 v146, v144, v145
	ds_read_b128 v[230:233], v5 offset:35328
	ds_read_b128 v[234:237], v5 offset:35584
	ds_read_b128 v[238:241], v5 offset:35840
	ds_read_b128 v[242:245], v5 offset:36096
	ds_read_b128 v[246:249], v5 offset:36352
	ds_read_b32 v250, v9 offset:35328
	v_add_f32_dpp v146, v146, v146 quad_perm:[1,0,3,2] row_mask:0xf bank_mask:0xf bound_ctrl:1
	v_pk_mul_f32 v[180:181], v[138:139], v[180:181]
	v_pk_fma_f32 v[180:181], v[140:141], v[182:183], v[180:181]
	v_add_f32_dpp v146, v146, v146 quad_perm:[2,3,0,1] row_mask:0xf bank_mask:0xf bound_ctrl:1
	v_add_f32 v152, v180, v181
	v_pk_mul_f32 v[198:199], v[198:199], v[206:207] op_sel_hi:[1,0]
	v_add_f32_dpp v146, v146, v146 row_half_mirror row_mask:0xf bank_mask:0xf bound_ctrl:1
	v_pk_mul_f32 v[200:201], v[200:201], v[206:207] op_sel_hi:[1,0]
	s_waitcnt lgkmcnt(6)
	v_add_f32_dpp v146, v146, v146 row_mirror row_mask:0xf bank_mask:0xf bound_ctrl:1
	v_pk_fma_f32 v[198:199], v[146:147], v[190:191], v[198:199] op_sel_hi:[0,1,1] neg_lo:[1,0,0] neg_hi:[1,0,0]
	v_pk_fma_f32 v[200:201], v[146:147], v[192:193], v[200:201] op_sel_hi:[0,1,1] neg_lo:[1,0,0] neg_hi:[1,0,0]
	v_pk_fma_f32 v[138:139], v[138:139], v[194:195], v[198:199]
	v_pk_fma_f32 v[140:141], v[140:141], v[196:197], v[200:201]
	v_pk_mul_f32 v[144:145], v[138:139], v[208:209]
	v_pk_fma_f32 v[144:145], v[140:141], v[210:211], v[144:145]
	v_add_f32 v146, v144, v145
	ds_read_b128 v[164:167], v5 offset:36864
	ds_read_b128 v[168:171], v5 offset:37120
	ds_read_b128 v[172:175], v5 offset:37376
	ds_read_b128 v[176:179], v5 offset:37632
	ds_read_b128 v[180:183], v5 offset:37888
	ds_read_b32 v184, v9 offset:36864
	v_add_f32_dpp v146, v146, v146 quad_perm:[1,0,3,2] row_mask:0xf bank_mask:0xf bound_ctrl:1
	v_pk_mul_f32 v[202:203], v[138:139], v[202:203]
	v_pk_fma_f32 v[202:203], v[140:141], v[204:205], v[202:203]
	v_add_f32_dpp v146, v146, v146 quad_perm:[2,3,0,1] row_mask:0xf bank_mask:0xf bound_ctrl:1
	v_add_f32 v153, v202, v203
	v_pk_mul_f32 v[220:221], v[220:221], v[228:229] op_sel_hi:[1,0]
	v_add_f32_dpp v146, v146, v146 row_half_mirror row_mask:0xf bank_mask:0xf bound_ctrl:1
	v_pk_mul_f32 v[222:223], v[222:223], v[228:229] op_sel_hi:[1,0]
	s_waitcnt lgkmcnt(6)
	v_add_f32_dpp v146, v146, v146 row_mirror row_mask:0xf bank_mask:0xf bound_ctrl:1
	v_pk_fma_f32 v[220:221], v[146:147], v[212:213], v[220:221] op_sel_hi:[0,1,1] neg_lo:[1,0,0] neg_hi:[1,0,0]
	v_pk_fma_f32 v[222:223], v[146:147], v[214:215], v[222:223] op_sel_hi:[0,1,1] neg_lo:[1,0,0] neg_hi:[1,0,0]
	v_pk_fma_f32 v[138:139], v[138:139], v[216:217], v[220:221]
	v_pk_fma_f32 v[140:141], v[140:141], v[218:219], v[222:223]
	v_pk_mul_f32 v[144:145], v[138:139], v[230:231]
	v_pk_fma_f32 v[144:145], v[140:141], v[232:233], v[144:145]
	v_add_f32 v146, v144, v145
	ds_read_b128 v[186:189], v5 offset:38400
	ds_read_b128 v[190:193], v5 offset:38656
	ds_read_b128 v[194:197], v5 offset:38912
	ds_read_b128 v[198:201], v5 offset:39168
	ds_read_b128 v[202:205], v5 offset:39424
	ds_read_b32 v206, v9 offset:38400
	v_add_f32_dpp v146, v146, v146 quad_perm:[1,0,3,2] row_mask:0xf bank_mask:0xf bound_ctrl:1
	v_pk_mul_f32 v[224:225], v[138:139], v[224:225]
	v_pk_fma_f32 v[224:225], v[140:141], v[226:227], v[224:225]
	v_add_f32_dpp v146, v146, v146 quad_perm:[2,3,0,1] row_mask:0xf bank_mask:0xf bound_ctrl:1
	v_add_f32 v154, v224, v225
	v_pk_mul_f32 v[242:243], v[242:243], v[250:251] op_sel_hi:[1,0]
	v_add_f32_dpp v146, v146, v146 row_half_mirror row_mask:0xf bank_mask:0xf bound_ctrl:1
	v_pk_mul_f32 v[244:245], v[244:245], v[250:251] op_sel_hi:[1,0]
	s_waitcnt lgkmcnt(6)
	v_add_f32_dpp v146, v146, v146 row_mirror row_mask:0xf bank_mask:0xf bound_ctrl:1
	v_pk_fma_f32 v[242:243], v[146:147], v[234:235], v[242:243] op_sel_hi:[0,1,1] neg_lo:[1,0,0] neg_hi:[1,0,0]
	v_pk_fma_f32 v[244:245], v[146:147], v[236:237], v[244:245] op_sel_hi:[0,1,1] neg_lo:[1,0,0] neg_hi:[1,0,0]
	v_pk_fma_f32 v[138:139], v[138:139], v[238:239], v[242:243]
	v_pk_fma_f32 v[140:141], v[140:141], v[240:241], v[244:245]
	v_pk_mul_f32 v[144:145], v[138:139], v[164:165]
	v_pk_fma_f32 v[144:145], v[140:141], v[166:167], v[144:145]
	v_add_f32 v146, v144, v145
	ds_read_b128 v[208:211], v5 offset:39936
	ds_read_b128 v[212:215], v5 offset:40192
	ds_read_b128 v[216:219], v5 offset:40448
	ds_read_b128 v[220:223], v5 offset:40704
	ds_read_b128 v[224:227], v5 offset:40960
	ds_read_b32 v228, v9 offset:39936
	v_add_f32_dpp v146, v146, v146 quad_perm:[1,0,3,2] row_mask:0xf bank_mask:0xf bound_ctrl:1
	v_pk_mul_f32 v[246:247], v[138:139], v[246:247]
	v_pk_fma_f32 v[246:247], v[140:141], v[248:249], v[246:247]
	v_add_f32_dpp v146, v146, v146 quad_perm:[2,3,0,1] row_mask:0xf bank_mask:0xf bound_ctrl:1
	v_add_f32 v155, v246, v247
	v_pk_mul_f32 v[176:177], v[176:177], v[184:185] op_sel_hi:[1,0]
	v_add_f32_dpp v146, v146, v146 row_half_mirror row_mask:0xf bank_mask:0xf bound_ctrl:1
	v_pk_mul_f32 v[178:179], v[178:179], v[184:185] op_sel_hi:[1,0]
	s_waitcnt lgkmcnt(6)
	v_add_f32_dpp v146, v146, v146 row_mirror row_mask:0xf bank_mask:0xf bound_ctrl:1
	v_pk_fma_f32 v[176:177], v[146:147], v[168:169], v[176:177] op_sel_hi:[0,1,1] neg_lo:[1,0,0] neg_hi:[1,0,0]
	v_pk_fma_f32 v[178:179], v[146:147], v[170:171], v[178:179] op_sel_hi:[0,1,1] neg_lo:[1,0,0] neg_hi:[1,0,0]
	v_pk_fma_f32 v[138:139], v[138:139], v[172:173], v[176:177]
	v_pk_fma_f32 v[140:141], v[140:141], v[174:175], v[178:179]
	v_pk_mul_f32 v[144:145], v[138:139], v[186:187]
	v_pk_fma_f32 v[144:145], v[140:141], v[188:189], v[144:145]
	v_add_f32 v146, v144, v145
	ds_read_b128 v[230:233], v5 offset:41472
	ds_read_b128 v[234:237], v5 offset:41728
	ds_read_b128 v[238:241], v5 offset:41984
	ds_read_b128 v[242:245], v5 offset:42240
	ds_read_b128 v[246:249], v5 offset:42496
	ds_read_b32 v250, v9 offset:41472
	v_add_f32_dpp v146, v146, v146 quad_perm:[1,0,3,2] row_mask:0xf bank_mask:0xf bound_ctrl:1
	v_pk_mul_f32 v[180:181], v[138:139], v[180:181]
	v_pk_fma_f32 v[180:181], v[140:141], v[182:183], v[180:181]
	v_add_f32_dpp v146, v146, v146 quad_perm:[2,3,0,1] row_mask:0xf bank_mask:0xf bound_ctrl:1
	v_add_f32 v156, v180, v181
	v_pk_mul_f32 v[198:199], v[198:199], v[206:207] op_sel_hi:[1,0]
	v_add_f32_dpp v146, v146, v146 row_half_mirror row_mask:0xf bank_mask:0xf bound_ctrl:1
	v_pk_mul_f32 v[200:201], v[200:201], v[206:207] op_sel_hi:[1,0]
	s_waitcnt lgkmcnt(6)
	v_add_f32_dpp v146, v146, v146 row_mirror row_mask:0xf bank_mask:0xf bound_ctrl:1
	v_pk_fma_f32 v[198:199], v[146:147], v[190:191], v[198:199] op_sel_hi:[0,1,1] neg_lo:[1,0,0] neg_hi:[1,0,0]
	v_pk_fma_f32 v[200:201], v[146:147], v[192:193], v[200:201] op_sel_hi:[0,1,1] neg_lo:[1,0,0] neg_hi:[1,0,0]
	v_pk_fma_f32 v[138:139], v[138:139], v[194:195], v[198:199]
	v_pk_fma_f32 v[140:141], v[140:141], v[196:197], v[200:201]
	v_pk_mul_f32 v[144:145], v[138:139], v[208:209]
	v_pk_fma_f32 v[144:145], v[140:141], v[210:211], v[144:145]
	v_add_f32 v146, v144, v145
	ds_read_b128 v[164:167], v5 offset:43008
	ds_read_b128 v[168:171], v5 offset:43264
	ds_read_b128 v[172:175], v5 offset:43520
	ds_read_b128 v[176:179], v5 offset:43776
	ds_read_b128 v[180:183], v5 offset:44032
	ds_read_b32 v184, v9 offset:43008
	v_add_f32_dpp v146, v146, v146 quad_perm:[1,0,3,2] row_mask:0xf bank_mask:0xf bound_ctrl:1
	v_pk_mul_f32 v[202:203], v[138:139], v[202:203]
	v_pk_fma_f32 v[202:203], v[140:141], v[204:205], v[202:203]
	v_add_f32_dpp v146, v146, v146 quad_perm:[2,3,0,1] row_mask:0xf bank_mask:0xf bound_ctrl:1
	v_add_f32 v157, v202, v203
	v_pk_mul_f32 v[220:221], v[220:221], v[228:229] op_sel_hi:[1,0]
	v_add_f32_dpp v146, v146, v146 row_half_mirror row_mask:0xf bank_mask:0xf bound_ctrl:1
	v_pk_mul_f32 v[222:223], v[222:223], v[228:229] op_sel_hi:[1,0]
	s_waitcnt lgkmcnt(6)
	v_add_f32_dpp v146, v146, v146 row_mirror row_mask:0xf bank_mask:0xf bound_ctrl:1
	v_pk_fma_f32 v[220:221], v[146:147], v[212:213], v[220:221] op_sel_hi:[0,1,1] neg_lo:[1,0,0] neg_hi:[1,0,0]
	v_pk_fma_f32 v[222:223], v[146:147], v[214:215], v[222:223] op_sel_hi:[0,1,1] neg_lo:[1,0,0] neg_hi:[1,0,0]
	v_pk_fma_f32 v[138:139], v[138:139], v[216:217], v[220:221]
	v_pk_fma_f32 v[140:141], v[140:141], v[218:219], v[222:223]
	v_pk_mul_f32 v[144:145], v[138:139], v[230:231]
	v_pk_fma_f32 v[144:145], v[140:141], v[232:233], v[144:145]
	v_add_f32 v146, v144, v145
	ds_read_b128 v[186:189], v5 offset:44544
	ds_read_b128 v[190:193], v5 offset:44800
	ds_read_b128 v[194:197], v5 offset:45056
	ds_read_b128 v[198:201], v5 offset:45312
	ds_read_b128 v[202:205], v5 offset:45568
	ds_read_b32 v206, v9 offset:44544
	v_add_f32_dpp v146, v146, v146 quad_perm:[1,0,3,2] row_mask:0xf bank_mask:0xf bound_ctrl:1
	v_pk_mul_f32 v[224:225], v[138:139], v[224:225]
	v_pk_fma_f32 v[224:225], v[140:141], v[226:227], v[224:225]
	v_add_f32_dpp v146, v146, v146 quad_perm:[2,3,0,1] row_mask:0xf bank_mask:0xf bound_ctrl:1
	v_add_f32 v158, v224, v225
	v_pk_mul_f32 v[242:243], v[242:243], v[250:251] op_sel_hi:[1,0]
	v_add_f32_dpp v146, v146, v146 row_half_mirror row_mask:0xf bank_mask:0xf bound_ctrl:1
	v_pk_mul_f32 v[244:245], v[244:245], v[250:251] op_sel_hi:[1,0]
	s_waitcnt lgkmcnt(6)
	v_add_f32_dpp v146, v146, v146 row_mirror row_mask:0xf bank_mask:0xf bound_ctrl:1
	v_pk_fma_f32 v[242:243], v[146:147], v[234:235], v[242:243] op_sel_hi:[0,1,1] neg_lo:[1,0,0] neg_hi:[1,0,0]
	v_pk_fma_f32 v[244:245], v[146:147], v[236:237], v[244:245] op_sel_hi:[0,1,1] neg_lo:[1,0,0] neg_hi:[1,0,0]
	v_pk_fma_f32 v[138:139], v[138:139], v[238:239], v[242:243]
	v_pk_fma_f32 v[140:141], v[140:141], v[240:241], v[244:245]
	v_pk_mul_f32 v[144:145], v[138:139], v[164:165]
	v_pk_fma_f32 v[144:145], v[140:141], v[166:167], v[144:145]
	v_add_f32 v146, v144, v145
	ds_read_b128 v[208:211], v5 offset:46080
	ds_read_b128 v[212:215], v5 offset:46336
	ds_read_b128 v[216:219], v5 offset:46592
	ds_read_b128 v[220:223], v5 offset:46848
	ds_read_b128 v[224:227], v5 offset:47104
	ds_read_b32 v228, v9 offset:46080
	v_add_f32_dpp v146, v146, v146 quad_perm:[1,0,3,2] row_mask:0xf bank_mask:0xf bound_ctrl:1
	v_pk_mul_f32 v[246:247], v[138:139], v[246:247]
	v_pk_fma_f32 v[246:247], v[140:141], v[248:249], v[246:247]
	v_add_f32_dpp v146, v146, v146 quad_perm:[2,3,0,1] row_mask:0xf bank_mask:0xf bound_ctrl:1
	v_add_f32 v159, v246, v247
	v_pk_mul_f32 v[176:177], v[176:177], v[184:185] op_sel_hi:[1,0]
	v_add_f32_dpp v146, v146, v146 row_half_mirror row_mask:0xf bank_mask:0xf bound_ctrl:1
	v_pk_mul_f32 v[178:179], v[178:179], v[184:185] op_sel_hi:[1,0]
	s_waitcnt lgkmcnt(6)
	v_add_f32_dpp v146, v146, v146 row_mirror row_mask:0xf bank_mask:0xf bound_ctrl:1
	v_pk_fma_f32 v[176:177], v[146:147], v[168:169], v[176:177] op_sel_hi:[0,1,1] neg_lo:[1,0,0] neg_hi:[1,0,0]
	v_pk_fma_f32 v[178:179], v[146:147], v[170:171], v[178:179] op_sel_hi:[0,1,1] neg_lo:[1,0,0] neg_hi:[1,0,0]
	v_pk_fma_f32 v[138:139], v[138:139], v[172:173], v[176:177]
	v_pk_fma_f32 v[140:141], v[140:141], v[174:175], v[178:179]
	v_pk_mul_f32 v[144:145], v[138:139], v[186:187]
	v_pk_fma_f32 v[144:145], v[140:141], v[188:189], v[144:145]
	v_add_f32 v146, v144, v145
	ds_read_b128 v[230:233], v5 offset:47616
	ds_read_b128 v[234:237], v5 offset:47872
	ds_read_b128 v[238:241], v5 offset:48128
	ds_read_b128 v[242:245], v5 offset:48384
	ds_read_b128 v[246:249], v5 offset:48640
	ds_read_b32 v250, v9 offset:47616
	v_add_f32_dpp v146, v146, v146 quad_perm:[1,0,3,2] row_mask:0xf bank_mask:0xf bound_ctrl:1
	v_pk_mul_f32 v[180:181], v[138:139], v[180:181]
	v_pk_fma_f32 v[180:181], v[140:141], v[182:183], v[180:181]
	v_add_f32_dpp v146, v146, v146 quad_perm:[2,3,0,1] row_mask:0xf bank_mask:0xf bound_ctrl:1
	v_add_f32 v160, v180, v181
	v_pk_mul_f32 v[198:199], v[198:199], v[206:207] op_sel_hi:[1,0]
	v_add_f32_dpp v146, v146, v146 row_half_mirror row_mask:0xf bank_mask:0xf bound_ctrl:1
	v_pk_mul_f32 v[200:201], v[200:201], v[206:207] op_sel_hi:[1,0]
	s_waitcnt lgkmcnt(6)
	v_add_f32_dpp v146, v146, v146 row_mirror row_mask:0xf bank_mask:0xf bound_ctrl:1
	v_pk_fma_f32 v[198:199], v[146:147], v[190:191], v[198:199] op_sel_hi:[0,1,1] neg_lo:[1,0,0] neg_hi:[1,0,0]
	v_pk_fma_f32 v[200:201], v[146:147], v[192:193], v[200:201] op_sel_hi:[0,1,1] neg_lo:[1,0,0] neg_hi:[1,0,0]
	v_pk_fma_f32 v[138:139], v[138:139], v[194:195], v[198:199]
	v_pk_fma_f32 v[140:141], v[140:141], v[196:197], v[200:201]
	v_pk_mul_f32 v[144:145], v[138:139], v[208:209]
	v_pk_fma_f32 v[144:145], v[140:141], v[210:211], v[144:145]
	v_add_f32 v146, v144, v145
	s_nop 1
	v_add_f32_dpp v146, v146, v146 quad_perm:[1,0,3,2] row_mask:0xf bank_mask:0xf bound_ctrl:1
	v_pk_mul_f32 v[202:203], v[138:139], v[202:203]
	v_pk_fma_f32 v[202:203], v[140:141], v[204:205], v[202:203]
	v_add_f32_dpp v146, v146, v146 quad_perm:[2,3,0,1] row_mask:0xf bank_mask:0xf bound_ctrl:1
	v_add_f32 v161, v202, v203
	v_pk_mul_f32 v[220:221], v[220:221], v[228:229] op_sel_hi:[1,0]
	v_add_f32_dpp v146, v146, v146 row_half_mirror row_mask:0xf bank_mask:0xf bound_ctrl:1
	v_pk_mul_f32 v[222:223], v[222:223], v[228:229] op_sel_hi:[1,0]
	s_waitcnt lgkmcnt(0)
	v_add_f32_dpp v146, v146, v146 row_mirror row_mask:0xf bank_mask:0xf bound_ctrl:1
	v_pk_fma_f32 v[220:221], v[146:147], v[212:213], v[220:221] op_sel_hi:[0,1,1] neg_lo:[1,0,0] neg_hi:[1,0,0]
	v_pk_fma_f32 v[222:223], v[146:147], v[214:215], v[222:223] op_sel_hi:[0,1,1] neg_lo:[1,0,0] neg_hi:[1,0,0]
	v_pk_fma_f32 v[138:139], v[138:139], v[216:217], v[220:221]
	v_pk_fma_f32 v[140:141], v[140:141], v[218:219], v[222:223]
	v_pk_mul_f32 v[144:145], v[138:139], v[230:231]
	v_pk_fma_f32 v[144:145], v[140:141], v[232:233], v[144:145]
	v_add_f32 v146, v144, v145
	s_nop 1
	v_add_f32_dpp v146, v146, v146 quad_perm:[1,0,3,2] row_mask:0xf bank_mask:0xf bound_ctrl:1
	v_pk_mul_f32 v[224:225], v[138:139], v[224:225]
	v_pk_fma_f32 v[224:225], v[140:141], v[226:227], v[224:225]
	v_add_f32_dpp v146, v146, v146 quad_perm:[2,3,0,1] row_mask:0xf bank_mask:0xf bound_ctrl:1
	v_add_f32 v162, v224, v225
	v_pk_mul_f32 v[242:243], v[242:243], v[250:251] op_sel_hi:[1,0]
	v_add_f32_dpp v146, v146, v146 row_half_mirror row_mask:0xf bank_mask:0xf bound_ctrl:1
	v_pk_mul_f32 v[244:245], v[244:245], v[250:251] op_sel_hi:[1,0]
	s_nop 0
	v_add_f32_dpp v146, v146, v146 row_mirror row_mask:0xf bank_mask:0xf bound_ctrl:1
	v_pk_fma_f32 v[242:243], v[146:147], v[234:235], v[242:243] op_sel_hi:[0,1,1] neg_lo:[1,0,0] neg_hi:[1,0,0]
	v_pk_fma_f32 v[244:245], v[146:147], v[236:237], v[244:245] op_sel_hi:[0,1,1] neg_lo:[1,0,0] neg_hi:[1,0,0]
	v_pk_fma_f32 v[138:139], v[138:139], v[238:239], v[242:243]
	v_pk_fma_f32 v[140:141], v[140:141], v[240:241], v[244:245]
	v_pk_mul_f32 v[246:247], v[138:139], v[246:247]
	v_pk_fma_f32 v[246:247], v[140:141], v[248:249], v[246:247]
	v_add_f32 v163, v246, v247
	s_nop 0
	v_add_f32_dpp v230, v148, v148 row_mirror row_mask:0xf bank_mask:0x3 bound_ctrl:1
	v_add_f32_dpp v230, v156, v156 row_mirror row_mask:0xf bank_mask:0xc bound_ctrl:1
	v_add_f32_dpp v231, v149, v149 row_mirror row_mask:0xf bank_mask:0x3 bound_ctrl:1
	v_add_f32_dpp v231, v157, v157 row_mirror row_mask:0xf bank_mask:0xc bound_ctrl:1
	v_add_f32_dpp v232, v150, v150 row_mirror row_mask:0xf bank_mask:0x3 bound_ctrl:1
	v_add_f32_dpp v232, v158, v158 row_mirror row_mask:0xf bank_mask:0xc bound_ctrl:1
	v_add_f32_dpp v233, v151, v151 row_mirror row_mask:0xf bank_mask:0x3 bound_ctrl:1
	v_add_f32_dpp v233, v159, v159 row_mirror row_mask:0xf bank_mask:0xc bound_ctrl:1
	v_add_f32_dpp v234, v152, v152 row_mirror row_mask:0xf bank_mask:0x3 bound_ctrl:1
	v_add_f32_dpp v234, v160, v160 row_mirror row_mask:0xf bank_mask:0xc bound_ctrl:1
	v_add_f32_dpp v235, v153, v153 row_mirror row_mask:0xf bank_mask:0x3 bound_ctrl:1
	v_add_f32_dpp v235, v161, v161 row_mirror row_mask:0xf bank_mask:0xc bound_ctrl:1
	v_add_f32_dpp v236, v154, v154 row_mirror row_mask:0xf bank_mask:0x3 bound_ctrl:1
	v_add_f32_dpp v236, v162, v162 row_mirror row_mask:0xf bank_mask:0xc bound_ctrl:1
	v_add_f32_dpp v237, v155, v155 row_mirror row_mask:0xf bank_mask:0x3 bound_ctrl:1
	v_add_f32_dpp v237, v163, v163 row_mirror row_mask:0xf bank_mask:0xc bound_ctrl:1
	v_add_f32_dpp v238, v230, v230 row_half_mirror row_mask:0xf bank_mask:0x5 bound_ctrl:1
	v_add_f32_dpp v238, v234, v234 row_half_mirror row_mask:0xf bank_mask:0xa bound_ctrl:1
	v_add_f32_dpp v239, v231, v231 row_half_mirror row_mask:0xf bank_mask:0x5 bound_ctrl:1
	v_add_f32_dpp v239, v235, v235 row_half_mirror row_mask:0xf bank_mask:0xa bound_ctrl:1
	v_add_f32_dpp v240, v232, v232 row_half_mirror row_mask:0xf bank_mask:0x5 bound_ctrl:1
	v_add_f32_dpp v240, v236, v236 row_half_mirror row_mask:0xf bank_mask:0xa bound_ctrl:1
	v_add_f32_dpp v241, v233, v233 row_half_mirror row_mask:0xf bank_mask:0x5 bound_ctrl:1
	v_add_f32_dpp v241, v237, v237 row_half_mirror row_mask:0xf bank_mask:0xa bound_ctrl:1
	v_and_b32 v244, 2, v3
	v_cmp_ne_u32 vcc, 0, v244
	v_cndmask_b32 v244, v240, v238, vcc
	v_cndmask_b32 v245, v241, v239, vcc
	v_cndmask_b32 v242, v238, v240, vcc
	v_cndmask_b32 v243, v239, v241, vcc
	v_add_f32_dpp v242, v244, v242 quad_perm:[2,3,0,1] row_mask:0xf bank_mask:0xf bound_ctrl:1
	v_add_f32_dpp v243, v245, v243 quad_perm:[2,3,0,1] row_mask:0xf bank_mask:0xf bound_ctrl:1
	v_and_b32 v244, 1, v3
	v_cmp_ne_u32 vcc, 0, v244
	v_cndmask_b32 v244, v243, v242, vcc
	v_cndmask_b32 v245, v242, v243, vcc
	s_nop 0
	v_add_f32_dpp v19, v244, v245 quad_perm:[1,0,3,2] row_mask:0xf bank_mask:0xf bound_ctrl:1
	v_mov_b32 v2, v138
	v_mov_b32 v13, v139
	v_mov_b32 v12, v140
	v_mov_b32 v8, v141

; #define SCAN_BAR() asm volatile("s_barrier" ::: "memory")
; __device__ __forceinline__ void scan_unit(const Ctx& C0, const float* scn, int T, int quarter, const float* S0, float* Sout, unsigned char* obase, int mode) {
;     ...
;             if (mode == 0) { *(float*)(obase + (size_t)(k * 32 + q) * UPITCH_B + rl * 4) = osel0; *(float*)(obase + (size_t)(k * 32 + 16 + q) * UPITCH_B + rl * 4) = osel1; }
;             SCAN_BAR();
	v_lshl_add_u64 v[14:15], v[6:7], 0, s[0:1]
	v_add_co_u32_e32 v16, vcc, 0xfc29000, v14
	s_mov_b32 s8, 0xfc7f000
	s_nop 0
	v_addc_co_u32_e32 v17, vcc, 0, v15, vcc
	global_store_dword v[16:17], v18, off offset:768
	v_add_co_u32_e32 v16, vcc, 0xfc54000, v14
	s_add_u32 s0, s0, 0xac000
	s_nop 0
	v_addc_co_u32_e32 v17, vcc, 0, v15, vcc
	global_store_dword v[16:17], v19, off offset:768
	s_barrier
	v_mov_b32 v138, v2
	v_mov_b32 v139, v13
	v_mov_b32 v140, v12
	v_mov_b32 v141, v8
	ds_read_b128 v[164:167], v10 offset:0
	ds_read_b128 v[168:171], v10 offset:256
	ds_read_b128 v[172:175], v10 offset:512
	ds_read_b128 v[176:179], v10 offset:768
	ds_read_b128 v[180:183], v10 offset:1024
	ds_read_b32 v184, v11 offset:0
	ds_read_b128 v[186:189], v10 offset:1536
	ds_read_b128 v[190:193], v10 offset:1792
	ds_read_b128 v[194:197], v10 offset:2048
	ds_read_b128 v[198:201], v10 offset:2304
	ds_read_b128 v[202:205], v10 offset:2560
	ds_read_b32 v206, v11 offset:1536
	s_waitcnt lgkmcnt(0)
	v_pk_mul_f32 v[144:145], v[138:139], v[164:165]
	v_pk_fma_f32 v[144:145], v[140:141], v[166:167], v[144:145]
	v_add_f32 v146, v144, v145
	ds_read_b128 v[208:211], v10 offset:3072
	ds_read_b128 v[212:215], v10 offset:3328
	ds_read_b128 v[216:219], v10 offset:3584
	ds_read_b128 v[220:223], v10 offset:3840
	ds_read_b128 v[224:227], v10 offset:4096
	ds_read_b32 v228, v11 offset:3072
	v_add_f32_dpp v146, v146, v146 quad_perm:[1,0,3,2] row_mask:0xf bank_mask:0xf bound_ctrl:1
	s_nop 0
	s_nop 0
	v_add_f32_dpp v146, v146, v146 quad_perm:[2,3,0,1] row_mask:0xf bank_mask:0xf bound_ctrl:1
	s_nop 0
	v_pk_mul_f32 v[176:177], v[176:177], v[184:185] op_sel_hi:[1,0]
	v_add_f32_dpp v146, v146, v146 row_half_mirror row_mask:0xf bank_mask:0xf bound_ctrl:1
	v_pk_mul_f32 v[178:179], v[178:179], v[184:185] op_sel_hi:[1,0]
	s_waitcnt lgkmcnt(6)
	v_add_f32_dpp v146, v146, v146 row_mirror row_mask:0xf bank_mask:0xf bound_ctrl:1
	v_pk_fma_f32 v[176:177], v[146:147], v[168:169], v[176:177] op_sel_hi:[0,1,1] neg_lo:[1,0,0] neg_hi:[1,0,0]
	v_pk_fma_f32 v[178:179], v[146:147], v[170:171], v[178:179] op_sel_hi:[0,1,1] neg_lo:[1,0,0] neg_hi:[1,0,0]
	v_pk_fma_f32 v[138:139], v[138:139], v[172:173], v[176:177]
	v_pk_fma_f32 v[140:141], v[140:141], v[174:175], v[178:179]
	v_pk_mul_f32 v[144:145], v[138:139], v[186:187]
	v_pk_fma_f32 v[144:145], v[140:141], v[188:189], v[144:145]
	v_add_f32 v146, v144, v145
	ds_read_b128 v[230:233], v10 offset:4608
	ds_read_b128 v[234:237], v10 offset:4864
	ds_read_b128 v[238:241], v10 offset:5120
	ds_read_b128 v[242:245], v10 offset:5376
	ds_read_b128 v[246:249], v10 offset:5632
	ds_read_b32 v250, v11 offset:4608
	v_add_f32_dpp v146, v146, v146 quad_perm:[1,0,3,2] row_mask:0xf bank_mask:0xf bound_ctrl:1
	v_pk_mul_f32 v[180:181], v[138:139], v[180:181]
	v_pk_fma_f32 v[180:181], v[140:141], v[182:183], v[180:181]
	v_add_f32_dpp v146, v146, v146 quad_perm:[2,3,0,1] row_mask:0xf bank_mask:0xf bound_ctrl:1
	v_add_f32 v148, v180, v181
	v_pk_mul_f32 v[198:199], v[198:199], v[206:207] op_sel_hi:[1,0]
	v_add_f32_dpp v146, v146, v146 row_half_mirror row_mask:0xf bank_mask:0xf bound_ctrl:1
	v_pk_mul_f32 v[200:201], v[200:201], v[206:207] op_sel_hi:[1,0]
	s_waitcnt lgkmcnt(6)
	v_add_f32_dpp v146, v146, v146 row_mirror row_mask:0xf bank_mask:0xf bound_ctrl:1
	v_pk_fma_f32 v[198:199], v[146:147], v[190:191], v[198:199] op_sel_hi:[0,1,1] neg_lo:[1,0,0] neg_hi:[1,0,0]
	v_pk_fma_f32 v[200:201], v[146:147], v[192:193], v[200:201] op_sel_hi:[0,1,1] neg_lo:[1,0,0] neg_hi:[1,0,0]
	v_pk_fma_f32 v[138:139], v[138:139], v[194:195], v[198:199]
	v_pk_fma_f32 v[140:141], v[140:141], v[196:197], v[200:201]
	v_pk_mul_f32 v[144:145], v[138:139], v[208:209]
	v_pk_fma_f32 v[144:145], v[140:141], v[210:211], v[144:145]
	v_add_f32 v146, v144, v145
	ds_read_b128 v[164:167], v10 offset:6144
	ds_read_b128 v[168:171], v10 offset:6400
	ds_read_b128 v[172:175], v10 offset:6656
	ds_read_b128 v[176:179], v10 offset:6912
	ds_read_b128 v[180:183], v10 offset:7168
	ds_read_b32 v184, v11 offset:6144
	v_add_f32_dpp v146, v146, v146 quad_perm:[1,0,3,2] row_mask:0xf bank_mask:0xf bound_ctrl:1
	v_pk_mul_f32 v[202:203], v[138:139], v[202:203]
	v_pk_fma_f32 v[202:203], v[140:141], v[204:205], v[202:203]
	v_add_f32_dpp v146, v146, v146 quad_perm:[2,3,0,1] row_mask:0xf bank_mask:0xf bound_ctrl:1
	v_add_f32 v149, v202, v203
	v_pk_mul_f32 v[220:221], v[220:221], v[228:229] op_sel_hi:[1,0]
	v_add_f32_dpp v146, v146, v146 row_half_mirror row_mask:0xf bank_mask:0xf bound_ctrl:1
	v_pk_mul_f32 v[222:223], v[222:223], v[228:229] op_sel_hi:[1,0]
	s_waitcnt lgkmcnt(6)
	v_add_f32_dpp v146, v146, v146 row_mirror row_mask:0xf bank_mask:0xf bound_ctrl:1
	v_pk_fma_f32 v[220:221], v[146:147], v[212:213], v[220:221] op_sel_hi:[0,1,1] neg_lo:[1,0,0] neg_hi:[1,0,0]
	v_pk_fma_f32 v[222:223], v[146:147], v[214:215], v[222:223] op_sel_hi:[0,1,1] neg_lo:[1,0,0] neg_hi:[1,0,0]
	v_pk_fma_f32 v[138:139], v[138:139], v[216:217], v[220:221]
	v_pk_fma_f32 v[140:141], v[140:141], v[218:219], v[222:223]
	v_pk_mul_f32 v[144:145], v[138:139], v[230:231]
	v_pk_fma_f32 v[144:145], v[140:141], v[232:233], v[144:145]
	v_add_f32 v146, v144, v145
	ds_read_b128 v[186:189], v10 offset:7680
	ds_read_b128 v[190:193], v10 offset:7936
	ds_read_b128 v[194:197], v10 offset:8192
	ds_read_b128 v[198:201], v10 offset:8448
	ds_read_b128 v[202:205], v10 offset:8704
	ds_read_b32 v206, v11 offset:7680
	v_add_f32_dpp v146, v146, v146 quad_perm:[1,0,3,2] row_mask:0xf bank_mask:0xf bound_ctrl:1
	v_pk_mul_f32 v[224:225], v[138:139], v[224:225]
	v_pk_fma_f32 v[224:225], v[140:141], v[226:227], v[224:225]
	v_add_f32_dpp v146, v146, v146 quad_perm:[2,3,0,1] row_mask:0xf bank_mask:0xf bound_ctrl:1
	v_add_f32 v150, v224, v225
	v_pk_mul_f32 v[242:243], v[242:243], v[250:251] op_sel_hi:[1,0]
	v_add_f32_dpp v146, v146, v146 row_half_mirror row_mask:0xf bank_mask:0xf bound_ctrl:1
	v_pk_mul_f32 v[244:245], v[244:245], v[250:251] op_sel_hi:[1,0]
	s_waitcnt lgkmcnt(6)
	v_add_f32_dpp v146, v146, v146 row_mirror row_mask:0xf bank_mask:0xf bound_ctrl:1
	v_pk_fma_f32 v[242:243], v[146:147], v[234:235], v[242:243] op_sel_hi:[0,1,1] neg_lo:[1,0,0] neg_hi:[1,0,0]
	v_pk_fma_f32 v[244:245], v[146:147], v[236:237], v[244:245] op_sel_hi:[0,1,1] neg_lo:[1,0,0] neg_hi:[1,0,0]
	v_pk_fma_f32 v[138:139], v[138:139], v[238:239], v[242:243]
	v_pk_fma_f32 v[140:141], v[140:141], v[240:241], v[244:245]
	v_pk_mul_f32 v[144:145], v[138:139], v[164:165]
	v_pk_fma_f32 v[144:145], v[140:141], v[166:167], v[144:145]
	v_add_f32 v146, v144, v145
	ds_read_b128 v[208:211], v10 offset:9216
	ds_read_b128 v[212:215], v10 offset:9472
	ds_read_b128 v[216:219], v10 offset:9728
	ds_read_b128 v[220:223], v10 offset:9984
	ds_read_b128 v[224:227], v10 offset:10240
	ds_read_b32 v228, v11 offset:9216
	v_add_f32_dpp v146, v146, v146 quad_perm:[1,0,3,2] row_mask:0xf bank_mask:0xf bound_ctrl:1
	v_pk_mul_f32 v[246:247], v[138:139], v[246:247]
	v_pk_fma_f32 v[246:247], v[140:141], v[248:249], v[246:247]
	v_add_f32_dpp v146, v146, v146 quad_perm:[2,3,0,1] row_mask:0xf bank_mask:0xf bound_ctrl:1
	v_add_f32 v151, v246, v247
	v_pk_mul_f32 v[176:177], v[176:177], v[184:185] op_sel_hi:[1,0]
	v_add_f32_dpp v146, v146, v146 row_half_mirror row_mask:0xf bank_mask:0xf bound_ctrl:1
	v_pk_mul_f32 v[178:179], v[178:179], v[184:185] op_sel_hi:[1,0]
	s_waitcnt lgkmcnt(6)
	v_add_f32_dpp v146, v146, v146 row_mirror row_mask:0xf bank_mask:0xf bound_ctrl:1
	v_pk_fma_f32 v[176:177], v[146:147], v[168:169], v[176:177] op_sel_hi:[0,1,1] neg_lo:[1,0,0] neg_hi:[1,0,0]
	v_pk_fma_f32 v[178:179], v[146:147], v[170:171], v[178:179] op_sel_hi:[0,1,1] neg_lo:[1,0,0] neg_hi:[1,0,0]
	v_pk_fma_f32 v[138:139], v[138:139], v[172:173], v[176:177]
	v_pk_fma_f32 v[140:141], v[140:141], v[174:175], v[178:179]
	v_pk_mul_f32 v[144:145], v[138:139], v[186:187]
	v_pk_fma_f32 v[144:145], v[140:141], v[188:189], v[144:145]
	v_add_f32 v146, v144, v145
	ds_read_b128 v[230:233], v10 offset:10752
	ds_read_b128 v[234:237], v10 offset:11008
	ds_read_b128 v[238:241], v10 offset:11264
	ds_read_b128 v[242:245], v10 offset:11520
	ds_read_b128 v[246:249], v10 offset:11776
	ds_read_b32 v250, v11 offset:10752
	v_add_f32_dpp v146, v146, v146 quad_perm:[1,0,3,2] row_mask:0xf bank_mask:0xf bound_ctrl:1
	v_pk_mul_f32 v[180:181], v[138:139], v[180:181]
	v_pk_fma_f32 v[180:181], v[140:141], v[182:183], v[180:181]
	v_add_f32_dpp v146, v146, v146 quad_perm:[2,3,0,1] row_mask:0xf bank_mask:0xf bound_ctrl:1
	v_add_f32 v152, v180, v181
	v_pk_mul_f32 v[198:199], v[198:199], v[206:207] op_sel_hi:[1,0]
	v_add_f32_dpp v146, v146, v146 row_half_mirror row_mask:0xf bank_mask:0xf bound_ctrl:1
	v_pk_mul_f32 v[200:201], v[200:201], v[206:207] op_sel_hi:[1,0]
	s_waitcnt lgkmcnt(6)
	v_add_f32_dpp v146, v146, v146 row_mirror row_mask:0xf bank_mask:0xf bound_ctrl:1
	v_pk_fma_f32 v[198:199], v[146:147], v[190:191], v[198:199] op_sel_hi:[0,1,1] neg_lo:[1,0,0] neg_hi:[1,0,0]
	v_pk_fma_f32 v[200:201], v[146:147], v[192:193], v[200:201] op_sel_hi:[0,1,1] neg_lo:[1,0,0] neg_hi:[1,0,0]
	v_pk_fma_f32 v[138:139], v[138:139], v[194:195], v[198:199]
	v_pk_fma_f32 v[140:141], v[140:141], v[196:197], v[200:201]
	v_pk_mul_f32 v[144:145], v[138:139], v[208:209]
	v_pk_fma_f32 v[144:145], v[140:141], v[210:211], v[144:145]
	v_add_f32 v146, v144, v145
	ds_read_b128 v[164:167], v10 offset:12288
	ds_read_b128 v[168:171], v10 offset:12544
	ds_read_b128 v[172:175], v10 offset:12800
	ds_read_b128 v[176:179], v10 offset:13056
	ds_read_b128 v[180:183], v10 offset:13312
	ds_read_b32 v184, v11 offset:12288
	v_add_f32_dpp v146, v146, v146 quad_perm:[1,0,3,2] row_mask:0xf bank_mask:0xf bound_ctrl:1
	v_pk_mul_f32 v[202:203], v[138:139], v[202:203]
	v_pk_fma_f32 v[202:203], v[140:141], v[204:205], v[202:203]
	v_add_f32_dpp v146, v146, v146 quad_perm:[2,3,0,1] row_mask:0xf bank_mask:0xf bound_ctrl:1
	v_add_f32 v153, v202, v203
	v_pk_mul_f32 v[220:221], v[220:221], v[228:229] op_sel_hi:[1,0]
	v_add_f32_dpp v146, v146, v146 row_half_mirror row_mask:0xf bank_mask:0xf bound_ctrl:1
	v_pk_mul_f32 v[222:223], v[222:223], v[228:229] op_sel_hi:[1,0]
	s_waitcnt lgkmcnt(6)
	v_add_f32_dpp v146, v146, v146 row_mirror row_mask:0xf bank_mask:0xf bound_ctrl:1
	v_pk_fma_f32 v[220:221], v[146:147], v[212:213], v[220:221] op_sel_hi:[0,1,1] neg_lo:[1,0,0] neg_hi:[1,0,0]
	v_pk_fma_f32 v[222:223], v[146:147], v[214:215], v[222:223] op_sel_hi:[0,1,1] neg_lo:[1,0,0] neg_hi:[1,0,0]
	v_pk_fma_f32 v[138:139], v[138:139], v[216:217], v[220:221]
	v_pk_fma_f32 v[140:141], v[140:141], v[218:219], v[222:223]
	v_pk_mul_f32 v[144:145], v[138:139], v[230:231]
	v_pk_fma_f32 v[144:145], v[140:141], v[232:233], v[144:145]
	v_add_f32 v146, v144, v145
	ds_read_b128 v[186:189], v10 offset:13824
	ds_read_b128 v[190:193], v10 offset:14080
	ds_read_b128 v[194:197], v10 offset:14336
	ds_read_b128 v[198:201], v10 offset:14592
	ds_read_b128 v[202:205], v10 offset:14848
	ds_read_b32 v206, v11 offset:13824
	v_add_f32_dpp v146, v146, v146 quad_perm:[1,0,3,2] row_mask:0xf bank_mask:0xf bound_ctrl:1
	v_pk_mul_f32 v[224:225], v[138:139], v[224:225]
	v_pk_fma_f32 v[224:225], v[140:141], v[226:227], v[224:225]
	v_add_f32_dpp v146, v146, v146 quad_perm:[2,3,0,1] row_mask:0xf bank_mask:0xf bound_ctrl:1
	v_add_f32 v154, v224, v225
	v_pk_mul_f32 v[242:243], v[242:243], v[250:251] op_sel_hi:[1,0]
	v_add_f32_dpp v146, v146, v146 row_half_mirror row_mask:0xf bank_mask:0xf bound_ctrl:1
	v_pk_mul_f32 v[244:245], v[244:245], v[250:251] op_sel_hi:[1,0]
	s_waitcnt lgkmcnt(6)
	v_add_f32_dpp v146, v146, v146 row_mirror row_mask:0xf bank_mask:0xf bound_ctrl:1
	v_pk_fma_f32 v[242:243], v[146:147], v[234:235], v[242:243] op_sel_hi:[0,1,1] neg_lo:[1,0,0] neg_hi:[1,0,0]
	v_pk_fma_f32 v[244:245], v[146:147], v[236:237], v[244:245] op_sel_hi:[0,1,1] neg_lo:[1,0,0] neg_hi:[1,0,0]
	v_pk_fma_f32 v[138:139], v[138:139], v[238:239], v[242:243]
	v_pk_fma_f32 v[140:141], v[140:141], v[240:241], v[244:245]
	v_pk_mul_f32 v[144:145], v[138:139], v[164:165]
	v_pk_fma_f32 v[144:145], v[140:141], v[166:167], v[144:145]
	v_add_f32 v146, v144, v145
	ds_read_b128 v[208:211], v10 offset:15360
	ds_read_b128 v[212:215], v10 offset:15616
	ds_read_b128 v[216:219], v10 offset:15872
	ds_read_b128 v[220:223], v10 offset:16128
	ds_read_b128 v[224:227], v10 offset:16384
	ds_read_b32 v228, v11 offset:15360
	v_add_f32_dpp v146, v146, v146 quad_perm:[1,0,3,2] row_mask:0xf bank_mask:0xf bound_ctrl:1
	v_pk_mul_f32 v[246:247], v[138:139], v[246:247]
	v_pk_fma_f32 v[246:247], v[140:141], v[248:249], v[246:247]
	v_add_f32_dpp v146, v146, v146 quad_perm:[2,3,0,1] row_mask:0xf bank_mask:0xf bound_ctrl:1
	v_add_f32 v155, v246, v247
	v_pk_mul_f32 v[176:177], v[176:177], v[184:185] op_sel_hi:[1,0]
	v_add_f32_dpp v146, v146, v146 row_half_mirror row_mask:0xf bank_mask:0xf bound_ctrl:1
	v_pk_mul_f32 v[178:179], v[178:179], v[184:185] op_sel_hi:[1,0]
	s_waitcnt lgkmcnt(6)
	v_add_f32_dpp v146, v146, v146 row_mirror row_mask:0xf bank_mask:0xf bound_ctrl:1
	v_pk_fma_f32 v[176:177], v[146:147], v[168:169], v[176:177] op_sel_hi:[0,1,1] neg_lo:[1,0,0] neg_hi:[1,0,0]
	v_pk_fma_f32 v[178:179], v[146:147], v[170:171], v[178:179] op_sel_hi:[0,1,1] neg_lo:[1,0,0] neg_hi:[1,0,0]
	v_pk_fma_f32 v[138:139], v[138:139], v[172:173], v[176:177]
	v_pk_fma_f32 v[140:141], v[140:141], v[174:175], v[178:179]
	v_pk_mul_f32 v[144:145], v[138:139], v[186:187]
	v_pk_fma_f32 v[144:145], v[140:141], v[188:189], v[144:145]
	v_add_f32 v146, v144, v145
	ds_read_b128 v[230:233], v10 offset:16896
	ds_read_b128 v[234:237], v10 offset:17152
	ds_read_b128 v[238:241], v10 offset:17408
	ds_read_b128 v[242:245], v10 offset:17664
	ds_read_b128 v[246:249], v10 offset:17920
	ds_read_b32 v250, v11 offset:16896
	v_add_f32_dpp v146, v146, v146 quad_perm:[1,0,3,2] row_mask:0xf bank_mask:0xf bound_ctrl:1
	v_pk_mul_f32 v[180:181], v[138:139], v[180:181]
	v_pk_fma_f32 v[180:181], v[140:141], v[182:183], v[180:181]
	v_add_f32_dpp v146, v146, v146 quad_perm:[2,3,0,1] row_mask:0xf bank_mask:0xf bound_ctrl:1
	v_add_f32 v156, v180, v181
	v_pk_mul_f32 v[198:199], v[198:199], v[206:207] op_sel_hi:[1,0]
	v_add_f32_dpp v146, v146, v146 row_half_mirror row_mask:0xf bank_mask:0xf bound_ctrl:1
	v_pk_mul_f32 v[200:201], v[200:201], v[206:207] op_sel_hi:[1,0]
	s_waitcnt lgkmcnt(6)
	v_add_f32_dpp v146, v146, v146 row_mirror row_mask:0xf bank_mask:0xf bound_ctrl:1
	v_pk_fma_f32 v[198:199], v[146:147], v[190:191], v[198:199] op_sel_hi:[0,1,1] neg_lo:[1,0,0] neg_hi:[1,0,0]
	v_pk_fma_f32 v[200:201], v[146:147], v[192:193], v[200:201] op_sel_hi:[0,1,1] neg_lo:[1,0,0] neg_hi:[1,0,0]
	v_pk_fma_f32 v[138:139], v[138:139], v[194:195], v[198:199]
	v_pk_fma_f32 v[140:141], v[140:141], v[196:197], v[200:201]
	v_pk_mul_f32 v[144:145], v[138:139], v[208:209]
	v_pk_fma_f32 v[144:145], v[140:141], v[210:211], v[144:145]
	v_add_f32 v146, v144, v145
	ds_read_b128 v[164:167], v10 offset:18432
	ds_read_b128 v[168:171], v10 offset:18688
	ds_read_b128 v[172:175], v10 offset:18944
	ds_read_b128 v[176:179], v10 offset:19200
	ds_read_b128 v[180:183], v10 offset:19456
	ds_read_b32 v184, v11 offset:18432
	v_add_f32_dpp v146, v146, v146 quad_perm:[1,0,3,2] row_mask:0xf bank_mask:0xf bound_ctrl:1
	v_pk_mul_f32 v[202:203], v[138:139], v[202:203]
	v_pk_fma_f32 v[202:203], v[140:141], v[204:205], v[202:203]
	v_add_f32_dpp v146, v146, v146 quad_perm:[2,3,0,1] row_mask:0xf bank_mask:0xf bound_ctrl:1
	v_add_f32 v157, v202, v203
	v_pk_mul_f32 v[220:221], v[220:221], v[228:229] op_sel_hi:[1,0]
	v_add_f32_dpp v146, v146, v146 row_half_mirror row_mask:0xf bank_mask:0xf bound_ctrl:1
	v_pk_mul_f32 v[222:223], v[222:223], v[228:229] op_sel_hi:[1,0]
	s_waitcnt lgkmcnt(6)
	v_add_f32_dpp v146, v146, v146 row_mirror row_mask:0xf bank_mask:0xf bound_ctrl:1
	v_pk_fma_f32 v[220:221], v[146:147], v[212:213], v[220:221] op_sel_hi:[0,1,1] neg_lo:[1,0,0] neg_hi:[1,0,0]
	v_pk_fma_f32 v[222:223], v[146:147], v[214:215], v[222:223] op_sel_hi:[0,1,1] neg_lo:[1,0,0] neg_hi:[1,0,0]
	v_pk_fma_f32 v[138:139], v[138:139], v[216:217], v[220:221]
	v_pk_fma_f32 v[140:141], v[140:141], v[218:219], v[222:223]
	v_pk_mul_f32 v[144:145], v[138:139], v[230:231]
	v_pk_fma_f32 v[144:145], v[140:141], v[232:233], v[144:145]
	v_add_f32 v146, v144, v145
	ds_read_b128 v[186:189], v10 offset:19968
	ds_read_b128 v[190:193], v10 offset:20224
	ds_read_b128 v[194:197], v10 offset:20480
	ds_read_b128 v[198:201], v10 offset:20736
	ds_read_b128 v[202:205], v10 offset:20992
	ds_read_b32 v206, v11 offset:19968
	v_add_f32_dpp v146, v146, v146 quad_perm:[1,0,3,2] row_mask:0xf bank_mask:0xf bound_ctrl:1
	v_pk_mul_f32 v[224:225], v[138:139], v[224:225]
	v_pk_fma_f32 v[224:225], v[140:141], v[226:227], v[224:225]
	v_add_f32_dpp v146, v146, v146 quad_perm:[2,3,0,1] row_mask:0xf bank_mask:0xf bound_ctrl:1
	v_add_f32 v158, v224, v225
	v_pk_mul_f32 v[242:243], v[242:243], v[250:251] op_sel_hi:[1,0]
	v_add_f32_dpp v146, v146, v146 row_half_mirror row_mask:0xf bank_mask:0xf bound_ctrl:1
	v_pk_mul_f32 v[244:245], v[244:245], v[250:251] op_sel_hi:[1,0]
	s_waitcnt lgkmcnt(6)
	v_add_f32_dpp v146, v146, v146 row_mirror row_mask:0xf bank_mask:0xf bound_ctrl:1
	v_pk_fma_f32 v[242:243], v[146:147], v[234:235], v[242:243] op_sel_hi:[0,1,1] neg_lo:[1,0,0] neg_hi:[1,0,0]
	v_pk_fma_f32 v[244:245], v[146:147], v[236:237], v[244:245] op_sel_hi:[0,1,1] neg_lo:[1,0,0] neg_hi:[1,0,0]
	v_pk_fma_f32 v[138:139], v[138:139], v[238:239], v[242:243]
	v_pk_fma_f32 v[140:141], v[140:141], v[240:241], v[244:245]
	v_pk_mul_f32 v[144:145], v[138:139], v[164:165]
	v_pk_fma_f32 v[144:145], v[140:141], v[166:167], v[144:145]
	v_add_f32 v146, v144, v145
	ds_read_b128 v[208:211], v10 offset:21504
	ds_read_b128 v[212:215], v10 offset:21760
	ds_read_b128 v[216:219], v10 offset:22016
	ds_read_b128 v[220:223], v10 offset:22272
	ds_read_b128 v[224:227], v10 offset:22528
	ds_read_b32 v228, v11 offset:21504
	v_add_f32_dpp v146, v146, v146 quad_perm:[1,0,3,2] row_mask:0xf bank_mask:0xf bound_ctrl:1
	v_pk_mul_f32 v[246:247], v[138:139], v[246:247]
	v_pk_fma_f32 v[246:247], v[140:141], v[248:249], v[246:247]
	v_add_f32_dpp v146, v146, v146 quad_perm:[2,3,0,1] row_mask:0xf bank_mask:0xf bound_ctrl:1
	v_add_f32 v159, v246, v247
	v_pk_mul_f32 v[176:177], v[176:177], v[184:185] op_sel_hi:[1,0]
	v_add_f32_dpp v146, v146, v146 row_half_mirror row_mask:0xf bank_mask:0xf bound_ctrl:1
	v_pk_mul_f32 v[178:179], v[178:179], v[184:185] op_sel_hi:[1,0]
	s_waitcnt lgkmcnt(6)
	v_add_f32_dpp v146, v146, v146 row_mirror row_mask:0xf bank_mask:0xf bound_ctrl:1
	v_pk_fma_f32 v[176:177], v[146:147], v[168:169], v[176:177] op_sel_hi:[0,1,1] neg_lo:[1,0,0] neg_hi:[1,0,0]
	v_pk_fma_f32 v[178:179], v[146:147], v[170:171], v[178:179] op_sel_hi:[0,1,1] neg_lo:[1,0,0] neg_hi:[1,0,0]
	v_pk_fma_f32 v[138:139], v[138:139], v[172:173], v[176:177]
	v_pk_fma_f32 v[140:141], v[140:141], v[174:175], v[178:179]
	v_pk_mul_f32 v[144:145], v[138:139], v[186:187]
	v_pk_fma_f32 v[144:145], v[140:141], v[188:189], v[144:145]
	v_add_f32 v146, v144, v145
	ds_read_b128 v[230:233], v10 offset:23040
	ds_read_b128 v[234:237], v10 offset:23296
	ds_read_b128 v[238:241], v10 offset:23552
	ds_read_b128 v[242:245], v10 offset:23808
	ds_read_b128 v[246:249], v10 offset:24064
	ds_read_b32 v250, v11 offset:23040
	v_add_f32_dpp v146, v146, v146 quad_perm:[1,0,3,2] row_mask:0xf bank_mask:0xf bound_ctrl:1
	v_pk_mul_f32 v[180:181], v[138:139], v[180:181]
	v_pk_fma_f32 v[180:181], v[140:141], v[182:183], v[180:181]
	v_add_f32_dpp v146, v146, v146 quad_perm:[2,3,0,1] row_mask:0xf bank_mask:0xf bound_ctrl:1
	v_add_f32 v160, v180, v181
	v_pk_mul_f32 v[198:199], v[198:199], v[206:207] op_sel_hi:[1,0]
	v_add_f32_dpp v146, v146, v146 row_half_mirror row_mask:0xf bank_mask:0xf bound_ctrl:1
	v_pk_mul_f32 v[200:201], v[200:201], v[206:207] op_sel_hi:[1,0]
	s_waitcnt lgkmcnt(6)
	v_add_f32_dpp v146, v146, v146 row_mirror row_mask:0xf bank_mask:0xf bound_ctrl:1
	v_pk_fma_f32 v[198:199], v[146:147], v[190:191], v[198:199] op_sel_hi:[0,1,1] neg_lo:[1,0,0] neg_hi:[1,0,0]
	v_pk_fma_f32 v[200:201], v[146:147], v[192:193], v[200:201] op_sel_hi:[0,1,1] neg_lo:[1,0,0] neg_hi:[1,0,0]
	v_pk_fma_f32 v[138:139], v[138:139], v[194:195], v[198:199]
	v_pk_fma_f32 v[140:141], v[140:141], v[196:197], v[200:201]
	v_pk_mul_f32 v[144:145], v[138:139], v[208:209]
	v_pk_fma_f32 v[144:145], v[140:141], v[210:211], v[144:145]
	v_add_f32 v146, v144, v145
	ds_read_b128 v[164:167], v10 offset:24576
	ds_read_b128 v[168:171], v10 offset:24832
	ds_read_b128 v[172:175], v10 offset:25088
	ds_read_b128 v[176:179], v10 offset:25344
	ds_read_b128 v[180:183], v10 offset:25600
	ds_read_b32 v184, v11 offset:24576
	v_add_f32_dpp v146, v146, v146 quad_perm:[1,0,3,2] row_mask:0xf bank_mask:0xf bound_ctrl:1
	v_pk_mul_f32 v[202:203], v[138:139], v[202:203]
	v_pk_fma_f32 v[202:203], v[140:141], v[204:205], v[202:203]
	v_add_f32_dpp v146, v146, v146 quad_perm:[2,3,0,1] row_mask:0xf bank_mask:0xf bound_ctrl:1
	v_add_f32 v161, v202, v203
	v_pk_mul_f32 v[220:221], v[220:221], v[228:229] op_sel_hi:[1,0]
	v_add_f32_dpp v146, v146, v146 row_half_mirror row_mask:0xf bank_mask:0xf bound_ctrl:1
	v_pk_mul_f32 v[222:223], v[222:223], v[228:229] op_sel_hi:[1,0]
	s_waitcnt lgkmcnt(6)
	v_add_f32_dpp v146, v146, v146 row_mirror row_mask:0xf bank_mask:0xf bound_ctrl:1
	v_pk_fma_f32 v[220:221], v[146:147], v[212:213], v[220:221] op_sel_hi:[0,1,1] neg_lo:[1,0,0] neg_hi:[1,0,0]
	v_pk_fma_f32 v[222:223], v[146:147], v[214:215], v[222:223] op_sel_hi:[0,1,1] neg_lo:[1,0,0] neg_hi:[1,0,0]
	v_pk_fma_f32 v[138:139], v[138:139], v[216:217], v[220:221]
	v_pk_fma_f32 v[140:141], v[140:141], v[218:219], v[222:223]
	v_pk_mul_f32 v[144:145], v[138:139], v[230:231]
	v_pk_fma_f32 v[144:145], v[140:141], v[232:233], v[144:145]
	v_add_f32 v146, v144, v145
	ds_read_b128 v[186:189], v10 offset:26112
	ds_read_b128 v[190:193], v10 offset:26368
	ds_read_b128 v[194:197], v10 offset:26624
	ds_read_b128 v[198:201], v10 offset:26880
	ds_read_b128 v[202:205], v10 offset:27136
	ds_read_b32 v206, v11 offset:26112
	v_add_f32_dpp v146, v146, v146 quad_perm:[1,0,3,2] row_mask:0xf bank_mask:0xf bound_ctrl:1
	v_pk_mul_f32 v[224:225], v[138:139], v[224:225]
	v_pk_fma_f32 v[224:225], v[140:141], v[226:227], v[224:225]
	v_add_f32_dpp v146, v146, v146 quad_perm:[2,3,0,1] row_mask:0xf bank_mask:0xf bound_ctrl:1
	v_add_f32 v162, v224, v225
	v_pk_mul_f32 v[242:243], v[242:243], v[250:251] op_sel_hi:[1,0]
	v_add_f32_dpp v146, v146, v146 row_half_mirror row_mask:0xf bank_mask:0xf bound_ctrl:1
	v_pk_mul_f32 v[244:245], v[244:245], v[250:251] op_sel_hi:[1,0]
	s_waitcnt lgkmcnt(6)
	v_add_f32_dpp v146, v146, v146 row_mirror row_mask:0xf bank_mask:0xf bound_ctrl:1
	v_pk_fma_f32 v[242:243], v[146:147], v[234:235], v[242:243] op_sel_hi:[0,1,1] neg_lo:[1,0,0] neg_hi:[1,0,0]
	v_pk_fma_f32 v[244:245], v[146:147], v[236:237], v[244:245] op_sel_hi:[0,1,1] neg_lo:[1,0,0] neg_hi:[1,0,0]
	v_pk_fma_f32 v[138:139], v[138:139], v[238:239], v[242:243]
	v_pk_fma_f32 v[140:141], v[140:141], v[240:241], v[244:245]
	v_pk_mul_f32 v[144:145], v[138:139], v[164:165]
	v_pk_fma_f32 v[144:145], v[140:141], v[166:167], v[144:145]
	v_add_f32 v146, v144, v145
	ds_read_b128 v[208:211], v10 offset:27648
	ds_read_b128 v[212:215], v10 offset:27904
	ds_read_b128 v[216:219], v10 offset:28160
	ds_read_b128 v[220:223], v10 offset:28416
	ds_read_b128 v[224:227], v10 offset:28672
	ds_read_b32 v228, v11 offset:27648
	v_add_f32_dpp v146, v146, v146 quad_perm:[1,0,3,2] row_mask:0xf bank_mask:0xf bound_ctrl:1
	v_pk_mul_f32 v[246:247], v[138:139], v[246:247]
	v_pk_fma_f32 v[246:247], v[140:141], v[248:249], v[246:247]
	v_add_f32_dpp v146, v146, v146 quad_perm:[2,3,0,1] row_mask:0xf bank_mask:0xf bound_ctrl:1
	v_add_f32 v163, v246, v247
	v_pk_mul_f32 v[176:177], v[176:177], v[184:185] op_sel_hi:[1,0]
	v_add_f32_dpp v146, v146, v146 row_half_mirror row_mask:0xf bank_mask:0xf bound_ctrl:1
	v_pk_mul_f32 v[178:179], v[178:179], v[184:185] op_sel_hi:[1,0]
	s_waitcnt lgkmcnt(6)
	v_add_f32_dpp v146, v146, v146 row_mirror row_mask:0xf bank_mask:0xf bound_ctrl:1
	v_pk_fma_f32 v[176:177], v[146:147], v[168:169], v[176:177] op_sel_hi:[0,1,1] neg_lo:[1,0,0] neg_hi:[1,0,0]
	v_pk_fma_f32 v[178:179], v[146:147], v[170:171], v[178:179] op_sel_hi:[0,1,1] neg_lo:[1,0,0] neg_hi:[1,0,0]
	v_pk_fma_f32 v[138:139], v[138:139], v[172:173], v[176:177]
	v_pk_fma_f32 v[140:141], v[140:141], v[174:175], v[178:179]
	v_pk_mul_f32 v[144:145], v[138:139], v[186:187]
	v_pk_fma_f32 v[144:145], v[140:141], v[188:189], v[144:145]
	v_add_f32 v146, v144, v145
	v_add_f32_dpp v230, v148, v148 row_mirror row_mask:0xf bank_mask:0x3 bound_ctrl:1
	v_add_f32_dpp v230, v156, v156 row_mirror row_mask:0xf bank_mask:0xc bound_ctrl:1
	v_add_f32_dpp v231, v149, v149 row_mirror row_mask:0xf bank_mask:0x3 bound_ctrl:1
	v_add_f32_dpp v231, v157, v157 row_mirror row_mask:0xf bank_mask:0xc bound_ctrl:1
	v_add_f32_dpp v232, v150, v150 row_mirror row_mask:0xf bank_mask:0x3 bound_ctrl:1
	v_add_f32_dpp v232, v158, v158 row_mirror row_mask:0xf bank_mask:0xc bound_ctrl:1
	v_add_f32_dpp v233, v151, v151 row_mirror row_mask:0xf bank_mask:0x3 bound_ctrl:1
	v_add_f32_dpp v233, v159, v159 row_mirror row_mask:0xf bank_mask:0xc bound_ctrl:1
	v_add_f32_dpp v234, v152, v152 row_mirror row_mask:0xf bank_mask:0x3 bound_ctrl:1
	v_add_f32_dpp v234, v160, v160 row_mirror row_mask:0xf bank_mask:0xc bound_ctrl:1
	v_add_f32_dpp v235, v153, v153 row_mirror row_mask:0xf bank_mask:0x3 bound_ctrl:1
	v_add_f32_dpp v235, v161, v161 row_mirror row_mask:0xf bank_mask:0xc bound_ctrl:1
	v_add_f32_dpp v236, v154, v154 row_mirror row_mask:0xf bank_mask:0x3 bound_ctrl:1
	v_add_f32_dpp v236, v162, v162 row_mirror row_mask:0xf bank_mask:0xc bound_ctrl:1
	v_add_f32_dpp v237, v155, v155 row_mirror row_mask:0xf bank_mask:0x3 bound_ctrl:1
	v_add_f32_dpp v237, v163, v163 row_mirror row_mask:0xf bank_mask:0xc bound_ctrl:1
	v_add_f32_dpp v238, v230, v230 row_half_mirror row_mask:0xf bank_mask:0x5 bound_ctrl:1
	v_add_f32_dpp v238, v234, v234 row_half_mirror row_mask:0xf bank_mask:0xa bound_ctrl:1
	v_add_f32_dpp v239, v231, v231 row_half_mirror row_mask:0xf bank_mask:0x5 bound_ctrl:1
	v_add_f32_dpp v239, v235, v235 row_half_mirror row_mask:0xf bank_mask:0xa bound_ctrl:1
	v_add_f32_dpp v240, v232, v232 row_half_mirror row_mask:0xf bank_mask:0x5 bound_ctrl:1
	v_add_f32_dpp v240, v236, v236 row_half_mirror row_mask:0xf bank_mask:0xa bound_ctrl:1
	v_add_f32_dpp v241, v233, v233 row_half_mirror row_mask:0xf bank_mask:0x5 bound_ctrl:1
	v_add_f32_dpp v241, v237, v237 row_half_mirror row_mask:0xf bank_mask:0xa bound_ctrl:1
	v_and_b32 v244, 2, v3
	v_cmp_ne_u32 vcc, 0, v244
	v_cndmask_b32 v244, v240, v238, vcc
	v_cndmask_b32 v245, v241, v239, vcc
	v_cndmask_b32 v242, v238, v240, vcc
	v_cndmask_b32 v243, v239, v241, vcc
	v_add_f32_dpp v242, v244, v242 quad_perm:[2,3,0,1] row_mask:0xf bank_mask:0xf bound_ctrl:1
	v_add_f32_dpp v243, v245, v243 quad_perm:[2,3,0,1] row_mask:0xf bank_mask:0xf bound_ctrl:1
	v_and_b32 v244, 1, v3
	v_cmp_ne_u32 vcc, 0, v244
	v_cndmask_b32 v244, v243, v242, vcc
	v_cndmask_b32 v245, v242, v243, vcc
	s_nop 0
	v_add_f32_dpp v18, v244, v245 quad_perm:[1,0,3,2] row_mask:0xf bank_mask:0xf bound_ctrl:1
	ds_read_b128 v[230:233], v10 offset:29184
	ds_read_b128 v[234:237], v10 offset:29440
	ds_read_b128 v[238:241], v10 offset:29696
	ds_read_b128 v[242:245], v10 offset:29952
	ds_read_b128 v[246:249], v10 offset:30208
	ds_read_b32 v250, v11 offset:29184
	v_add_f32_dpp v146, v146, v146 quad_perm:[1,0,3,2] row_mask:0xf bank_mask:0xf bound_ctrl:1
	v_pk_mul_f32 v[180:181], v[138:139], v[180:181]
	v_pk_fma_f32 v[180:181], v[140:141], v[182:183], v[180:181]
	v_add_f32_dpp v146, v146, v146 quad_perm:[2,3,0,1] row_mask:0xf bank_mask:0xf bound_ctrl:1
	v_add_f32 v148, v180, v181
	v_pk_mul_f32 v[198:199], v[198:199], v[206:207] op_sel_hi:[1,0]
	v_add_f32_dpp v146, v146, v146 row_half_mirror row_mask:0xf bank_mask:0xf bound_ctrl:1
	v_pk_mul_f32 v[200:201], v[200:201], v[206:207] op_sel_hi:[1,0]
	s_waitcnt lgkmcnt(6)
	v_add_f32_dpp v146, v146, v146 row_mirror row_mask:0xf bank_mask:0xf bound_ctrl:1
	v_pk_fma_f32 v[198:199], v[146:147], v[190:191], v[198:199] op_sel_hi:[0,1,1] neg_lo:[1,0,0] neg_hi:[1,0,0]
	v_pk_fma_f32 v[200:201], v[146:147], v[192:193], v[200:201] op_sel_hi:[0,1,1] neg_lo:[1,0,0] neg_hi:[1,0,0]
	v_pk_fma_f32 v[138:139], v[138:139], v[194:195], v[198:199]
	v_pk_fma_f32 v[140:141], v[140:141], v[196:197], v[200:201]
	v_pk_mul_f32 v[144:145], v[138:139], v[208:209]
	v_pk_fma_f32 v[144:145], v[140:141], v[210:211], v[144:145]
	v_add_f32 v146, v144, v145
	ds_read_b128 v[164:167], v10 offset:30720
	ds_read_b128 v[168:171], v10 offset:30976
	ds_read_b128 v[172:175], v10 offset:31232
	ds_read_b128 v[176:179], v10 offset:31488
	ds_read_b128 v[180:183], v10 offset:31744
	ds_read_b32 v184, v11 offset:30720
	v_add_f32_dpp v146, v146, v146 quad_perm:[1,0,3,2] row_mask:0xf bank_mask:0xf bound_ctrl:1
	v_pk_mul_f32 v[202:203], v[138:139], v[202:203]
	v_pk_fma_f32 v[202:203], v[140:141], v[204:205], v[202:203]
	v_add_f32_dpp v146, v146, v146 quad_perm:[2,3,0,1] row_mask:0xf bank_mask:0xf bound_ctrl:1
	v_add_f32 v149, v202, v203
	v_pk_mul_f32 v[220:221], v[220:221], v[228:229] op_sel_hi:[1,0]
	v_add_f32_dpp v146, v146, v146 row_half_mirror row_mask:0xf bank_mask:0xf bound_ctrl:1
	v_pk_mul_f32 v[222:223], v[222:223], v[228:229] op_sel_hi:[1,0]
	s_waitcnt lgkmcnt(6)
	v_add_f32_dpp v146, v146, v146 row_mirror row_mask:0xf bank_mask:0xf bound_ctrl:1
	v_pk_fma_f32 v[220:221], v[146:147], v[212:213], v[220:221] op_sel_hi:[0,1,1] neg_lo:[1,0,0] neg_hi:[1,0,0]
	v_pk_fma_f32 v[222:223], v[146:147], v[214:215], v[222:223] op_sel_hi:[0,1,1] neg_lo:[1,0,0] neg_hi:[1,0,0]
	v_pk_fma_f32 v[138:139], v[138:139], v[216:217], v[220:221]
	v_pk_fma_f32 v[140:141], v[140:141], v[218:219], v[222:223]
	v_pk_mul_f32 v[144:145], v[138:139], v[230:231]
	v_pk_fma_f32 v[144:145], v[140:141], v[232:233], v[144:145]
	v_add_f32 v146, v144, v145
	ds_read_b128 v[186:189], v10 offset:32256
	ds_read_b128 v[190:193], v10 offset:32512
	ds_read_b128 v[194:197], v10 offset:32768
	ds_read_b128 v[198:201], v10 offset:33024
	ds_read_b128 v[202:205], v10 offset:33280
	ds_read_b32 v206, v11 offset:32256
	v_add_f32_dpp v146, v146, v146 quad_perm:[1,0,3,2] row_mask:0xf bank_mask:0xf bound_ctrl:1
	v_pk_mul_f32 v[224:225], v[138:139], v[224:225]
	v_pk_fma_f32 v[224:225], v[140:141], v[226:227], v[224:225]
	v_add_f32_dpp v146, v146, v146 quad_perm:[2,3,0,1] row_mask:0xf bank_mask:0xf bound_ctrl:1
	v_add_f32 v150, v224, v225
	v_pk_mul_f32 v[242:243], v[242:243], v[250:251] op_sel_hi:[1,0]
	v_add_f32_dpp v146, v146, v146 row_half_mirror row_mask:0xf bank_mask:0xf bound_ctrl:1
	v_pk_mul_f32 v[244:245], v[244:245], v[250:251] op_sel_hi:[1,0]
	s_waitcnt lgkmcnt(6)
	v_add_f32_dpp v146, v146, v146 row_mirror row_mask:0xf bank_mask:0xf bound_ctrl:1
	v_pk_fma_f32 v[242:243], v[146:147], v[234:235], v[242:243] op_sel_hi:[0,1,1] neg_lo:[1,0,0] neg_hi:[1,0,0]
	v_pk_fma_f32 v[244:245], v[146:147], v[236:237], v[244:245] op_sel_hi:[0,1,1] neg_lo:[1,0,0] neg_hi:[1,0,0]
	v_pk_fma_f32 v[138:139], v[138:139], v[238:239], v[242:243]
	v_pk_fma_f32 v[140:141], v[140:141], v[240:241], v[244:245]
	v_pk_mul_f32 v[144:145], v[138:139], v[164:165]
	v_pk_fma_f32 v[144:145], v[140:141], v[166:167], v[144:145]
	v_add_f32 v146, v144, v145
	ds_read_b128 v[208:211], v10 offset:33792
	ds_read_b128 v[212:215], v10 offset:34048
	ds_read_b128 v[216:219], v10 offset:34304
	ds_read_b128 v[220:223], v10 offset:34560
	ds_read_b128 v[224:227], v10 offset:34816
	ds_read_b32 v228, v11 offset:33792
	v_add_f32_dpp v146, v146, v146 quad_perm:[1,0,3,2] row_mask:0xf bank_mask:0xf bound_ctrl:1
	v_pk_mul_f32 v[246:247], v[138:139], v[246:247]
	v_pk_fma_f32 v[246:247], v[140:141], v[248:249], v[246:247]
	v_add_f32_dpp v146, v146, v146 quad_perm:[2,3,0,1] row_mask:0xf bank_mask:0xf bound_ctrl:1
	v_add_f32 v151, v246, v247
	v_pk_mul_f32 v[176:177], v[176:177], v[184:185] op_sel_hi:[1,0]
	v_add_f32_dpp v146, v146, v146 row_half_mirror row_mask:0xf bank_mask:0xf bound_ctrl:1
	v_pk_mul_f32 v[178:179], v[178:179], v[184:185] op_sel_hi:[1,0]
	s_waitcnt lgkmcnt(6)
	v_add_f32_dpp v146, v146, v146 row_mirror row_mask:0xf bank_mask:0xf bound_ctrl:1
	v_pk_fma_f32 v[176:177], v[146:147], v[168:169], v[176:177] op_sel_hi:[0,1,1] neg_lo:[1,0,0] neg_hi:[1,0,0]
	v_pk_fma_f32 v[178:179], v[146:147], v[170:171], v[178:179] op_sel_hi:[0,1,1] neg_lo:[1,0,0] neg_hi:[1,0,0]
	v_pk_fma_f32 v[138:139], v[138:139], v[172:173], v[176:177]
	v_pk_fma_f32 v[140:141], v[140:141], v[174:175], v[178:179]
	v_pk_mul_f32 v[144:145], v[138:139], v[186:187]
	v_pk_fma_f32 v[144:145], v[140:141], v[188:189], v[144:145]
	v_add_f32 v146, v144, v145
	ds_read_b128 v[230:233], v10 offset:35328
	ds_read_b128 v[234:237], v10 offset:35584
	ds_read_b128 v[238:241], v10 offset:35840
	ds_read_b128 v[242:245], v10 offset:36096
	ds_read_b128 v[246:249], v10 offset:36352
	ds_read_b32 v250, v11 offset:35328
	v_add_f32_dpp v146, v146, v146 quad_perm:[1,0,3,2] row_mask:0xf bank_mask:0xf bound_ctrl:1
	v_pk_mul_f32 v[180:181], v[138:139], v[180:181]
	v_pk_fma_f32 v[180:181], v[140:141], v[182:183], v[180:181]
	v_add_f32_dpp v146, v146, v146 quad_perm:[2,3,0,1] row_mask:0xf bank_mask:0xf bound_ctrl:1
	v_add_f32 v152, v180, v181
	v_pk_mul_f32 v[198:199], v[198:199], v[206:207] op_sel_hi:[1,0]
	v_add_f32_dpp v146, v146, v146 row_half_mirror row_mask:0xf bank_mask:0xf bound_ctrl:1
	v_pk_mul_f32 v[200:201], v[200:201], v[206:207] op_sel_hi:[1,0]
	s_waitcnt lgkmcnt(6)
	v_add_f32_dpp v146, v146, v146 row_mirror row_mask:0xf bank_mask:0xf bound_ctrl:1
	v_pk_fma_f32 v[198:199], v[146:147], v[190:191], v[198:199] op_sel_hi:[0,1,1] neg_lo:[1,0,0] neg_hi:[1,0,0]
	v_pk_fma_f32 v[200:201], v[146:147], v[192:193], v[200:201] op_sel_hi:[0,1,1] neg_lo:[1,0,0] neg_hi:[1,0,0]
	v_pk_fma_f32 v[138:139], v[138:139], v[194:195], v[198:199]
	v_pk_fma_f32 v[140:141], v[140:141], v[196:197], v[200:201]
	v_pk_mul_f32 v[144:145], v[138:139], v[208:209]
	v_pk_fma_f32 v[144:145], v[140:141], v[210:211], v[144:145]
	v_add_f32 v146, v144, v145
	ds_read_b128 v[164:167], v10 offset:36864
	ds_read_b128 v[168:171], v10 offset:37120
	ds_read_b128 v[172:175], v10 offset:37376
	ds_read_b128 v[176:179], v10 offset:37632
	ds_read_b128 v[180:183], v10 offset:37888
	ds_read_b32 v184, v11 offset:36864
	v_add_f32_dpp v146, v146, v146 quad_perm:[1,0,3,2] row_mask:0xf bank_mask:0xf bound_ctrl:1
	v_pk_mul_f32 v[202:203], v[138:139], v[202:203]
	v_pk_fma_f32 v[202:203], v[140:141], v[204:205], v[202:203]
	v_add_f32_dpp v146, v146, v146 quad_perm:[2,3,0,1] row_mask:0xf bank_mask:0xf bound_ctrl:1
	v_add_f32 v153, v202, v203
	v_pk_mul_f32 v[220:221], v[220:221], v[228:229] op_sel_hi:[1,0]
	v_add_f32_dpp v146, v146, v146 row_half_mirror row_mask:0xf bank_mask:0xf bound_ctrl:1
	v_pk_mul_f32 v[222:223], v[222:223], v[228:229] op_sel_hi:[1,0]
	s_waitcnt lgkmcnt(6)
	v_add_f32_dpp v146, v146, v146 row_mirror row_mask:0xf bank_mask:0xf bound_ctrl:1
	v_pk_fma_f32 v[220:221], v[146:147], v[212:213], v[220:221] op_sel_hi:[0,1,1] neg_lo:[1,0,0] neg_hi:[1,0,0]
	v_pk_fma_f32 v[222:223], v[146:147], v[214:215], v[222:223] op_sel_hi:[0,1,1] neg_lo:[1,0,0] neg_hi:[1,0,0]
	v_pk_fma_f32 v[138:139], v[138:139], v[216:217], v[220:221]
	v_pk_fma_f32 v[140:141], v[140:141], v[218:219], v[222:223]
	v_pk_mul_f32 v[144:145], v[138:139], v[230:231]
	v_pk_fma_f32 v[144:145], v[140:141], v[232:233], v[144:145]
	v_add_f32 v146, v144, v145
	ds_read_b128 v[186:189], v10 offset:38400
	ds_read_b128 v[190:193], v10 offset:38656
	ds_read_b128 v[194:197], v10 offset:38912
	ds_read_b128 v[198:201], v10 offset:39168
	ds_read_b128 v[202:205], v10 offset:39424
	ds_read_b32 v206, v11 offset:38400
	v_add_f32_dpp v146, v146, v146 quad_perm:[1,0,3,2] row_mask:0xf bank_mask:0xf bound_ctrl:1
	v_pk_mul_f32 v[224:225], v[138:139], v[224:225]
	v_pk_fma_f32 v[224:225], v[140:141], v[226:227], v[224:225]
	v_add_f32_dpp v146, v146, v146 quad_perm:[2,3,0,1] row_mask:0xf bank_mask:0xf bound_ctrl:1
	v_add_f32 v154, v224, v225
	v_pk_mul_f32 v[242:243], v[242:243], v[250:251] op_sel_hi:[1,0]
	v_add_f32_dpp v146, v146, v146 row_half_mirror row_mask:0xf bank_mask:0xf bound_ctrl:1
	v_pk_mul_f32 v[244:245], v[244:245], v[250:251] op_sel_hi:[1,0]
	s_waitcnt lgkmcnt(6)
	v_add_f32_dpp v146, v146, v146 row_mirror row_mask:0xf bank_mask:0xf bound_ctrl:1
	v_pk_fma_f32 v[242:243], v[146:147], v[234:235], v[242:243] op_sel_hi:[0,1,1] neg_lo:[1,0,0] neg_hi:[1,0,0]
	v_pk_fma_f32 v[244:245], v[146:147], v[236:237], v[244:245] op_sel_hi:[0,1,1] neg_lo:[1,0,0] neg_hi:[1,0,0]
	v_pk_fma_f32 v[138:139], v[138:139], v[238:239], v[242:243]
	v_pk_fma_f32 v[140:141], v[140:141], v[240:241], v[244:245]
	v_pk_mul_f32 v[144:145], v[138:139], v[164:165]
	v_pk_fma_f32 v[144:145], v[140:141], v[166:167], v[144:145]
	v_add_f32 v146, v144, v145
	ds_read_b128 v[208:211], v10 offset:39936
	ds_read_b128 v[212:215], v10 offset:40192
	ds_read_b128 v[216:219], v10 offset:40448
	ds_read_b128 v[220:223], v10 offset:40704
	ds_read_b128 v[224:227], v10 offset:40960
	ds_read_b32 v228, v11 offset:39936
	v_add_f32_dpp v146, v146, v146 quad_perm:[1,0,3,2] row_mask:0xf bank_mask:0xf bound_ctrl:1
	v_pk_mul_f32 v[246:247], v[138:139], v[246:247]
	v_pk_fma_f32 v[246:247], v[140:141], v[248:249], v[246:247]
	v_add_f32_dpp v146, v146, v146 quad_perm:[2,3,0,1] row_mask:0xf bank_mask:0xf bound_ctrl:1
	v_add_f32 v155, v246, v247
	v_pk_mul_f32 v[176:177], v[176:177], v[184:185] op_sel_hi:[1,0]
	v_add_f32_dpp v146, v146, v146 row_half_mirror row_mask:0xf bank_mask:0xf bound_ctrl:1
	v_pk_mul_f32 v[178:179], v[178:179], v[184:185] op_sel_hi:[1,0]
	s_waitcnt lgkmcnt(6)
	v_add_f32_dpp v146, v146, v146 row_mirror row_mask:0xf bank_mask:0xf bound_ctrl:1
	v_pk_fma_f32 v[176:177], v[146:147], v[168:169], v[176:177] op_sel_hi:[0,1,1] neg_lo:[1,0,0] neg_hi:[1,0,0]
	v_pk_fma_f32 v[178:179], v[146:147], v[170:171], v[178:179] op_sel_hi:[0,1,1] neg_lo:[1,0,0] neg_hi:[1,0,0]
	v_pk_fma_f32 v[138:139], v[138:139], v[172:173], v[176:177]
	v_pk_fma_f32 v[140:141], v[140:141], v[174:175], v[178:179]
	v_pk_mul_f32 v[144:145], v[138:139], v[186:187]
	v_pk_fma_f32 v[144:145], v[140:141], v[188:189], v[144:145]
	v_add_f32 v146, v144, v145
	ds_read_b128 v[230:233], v10 offset:41472
	ds_read_b128 v[234:237], v10 offset:41728
	ds_read_b128 v[238:241], v10 offset:41984
	ds_read_b128 v[242:245], v10 offset:42240
	ds_read_b128 v[246:249], v10 offset:42496
	ds_read_b32 v250, v11 offset:41472
	v_add_f32_dpp v146, v146, v146 quad_perm:[1,0,3,2] row_mask:0xf bank_mask:0xf bound_ctrl:1
	v_pk_mul_f32 v[180:181], v[138:139], v[180:181]
	v_pk_fma_f32 v[180:181], v[140:141], v[182:183], v[180:181]
	v_add_f32_dpp v146, v146, v146 quad_perm:[2,3,0,1] row_mask:0xf bank_mask:0xf bound_ctrl:1
	v_add_f32 v156, v180, v181
	v_pk_mul_f32 v[198:199], v[198:199], v[206:207] op_sel_hi:[1,0]
	v_add_f32_dpp v146, v146, v146 row_half_mirror row_mask:0xf bank_mask:0xf bound_ctrl:1
	v_pk_mul_f32 v[200:201], v[200:201], v[206:207] op_sel_hi:[1,0]
	s_waitcnt lgkmcnt(6)
	v_add_f32_dpp v146, v146, v146 row_mirror row_mask:0xf bank_mask:0xf bound_ctrl:1
	v_pk_fma_f32 v[198:199], v[146:147], v[190:191], v[198:199] op_sel_hi:[0,1,1] neg_lo:[1,0,0] neg_hi:[1,0,0]
	v_pk_fma_f32 v[200:201], v[146:147], v[192:193], v[200:201] op_sel_hi:[0,1,1] neg_lo:[1,0,0] neg_hi:[1,0,0]
	v_pk_fma_f32 v[138:139], v[138:139], v[194:195], v[198:199]
	v_pk_fma_f32 v[140:141], v[140:141], v[196:197], v[200:201]
	v_pk_mul_f32 v[144:145], v[138:139], v[208:209]
	v_pk_fma_f32 v[144:145], v[140:141], v[210:211], v[144:145]
	v_add_f32 v146, v144, v145
	ds_read_b128 v[164:167], v10 offset:43008
	ds_read_b128 v[168:171], v10 offset:43264
	ds_read_b128 v[172:175], v10 offset:43520
	ds_read_b128 v[176:179], v10 offset:43776
	ds_read_b128 v[180:183], v10 offset:44032
	ds_read_b32 v184, v11 offset:43008
	v_add_f32_dpp v146, v146, v146 quad_perm:[1,0,3,2] row_mask:0xf bank_mask:0xf bound_ctrl:1
	v_pk_mul_f32 v[202:203], v[138:139], v[202:203]
	v_pk_fma_f32 v[202:203], v[140:141], v[204:205], v[202:203]
	v_add_f32_dpp v146, v146, v146 quad_perm:[2,3,0,1] row_mask:0xf bank_mask:0xf bound_ctrl:1
	v_add_f32 v157, v202, v203
	v_pk_mul_f32 v[220:221], v[220:221], v[228:229] op_sel_hi:[1,0]
	v_add_f32_dpp v146, v146, v146 row_half_mirror row_mask:0xf bank_mask:0xf bound_ctrl:1
	v_pk_mul_f32 v[222:223], v[222:223], v[228:229] op_sel_hi:[1,0]
	s_waitcnt lgkmcnt(6)
	v_add_f32_dpp v146, v146, v146 row_mirror row_mask:0xf bank_mask:0xf bound_ctrl:1
	v_pk_fma_f32 v[220:221], v[146:147], v[212:213], v[220:221] op_sel_hi:[0,1,1] neg_lo:[1,0,0] neg_hi:[1,0,0]
	v_pk_fma_f32 v[222:223], v[146:147], v[214:215], v[222:223] op_sel_hi:[0,1,1] neg_lo:[1,0,0] neg_hi:[1,0,0]
	v_pk_fma_f32 v[138:139], v[138:139], v[216:217], v[220:221]
	v_pk_fma_f32 v[140:141], v[140:141], v[218:219], v[222:223]
	v_pk_mul_f32 v[144:145], v[138:139], v[230:231]
	v_pk_fma_f32 v[144:145], v[140:141], v[232:233], v[144:145]
	v_add_f32 v146, v144, v145
	ds_read_b128 v[186:189], v10 offset:44544
	ds_read_b128 v[190:193], v10 offset:44800
	ds_read_b128 v[194:197], v10 offset:45056
	ds_read_b128 v[198:201], v10 offset:45312
	ds_read_b128 v[202:205], v10 offset:45568
	ds_read_b32 v206, v11 offset:44544
	v_add_f32_dpp v146, v146, v146 quad_perm:[1,0,3,2] row_mask:0xf bank_mask:0xf bound_ctrl:1
	v_pk_mul_f32 v[224:225], v[138:139], v[224:225]
	v_pk_fma_f32 v[224:225], v[140:141], v[226:227], v[224:225]
	v_add_f32_dpp v146, v146, v146 quad_perm:[2,3,0,1] row_mask:0xf bank_mask:0xf bound_ctrl:1
	v_add_f32 v158, v224, v225
	v_pk_mul_f32 v[242:243], v[242:243], v[250:251] op_sel_hi:[1,0]
	v_add_f32_dpp v146, v146, v146 row_half_mirror row_mask:0xf bank_mask:0xf bound_ctrl:1
	v_pk_mul_f32 v[244:245], v[244:245], v[250:251] op_sel_hi:[1,0]
	s_waitcnt lgkmcnt(6)
	v_add_f32_dpp v146, v146, v146 row_mirror row_mask:0xf bank_mask:0xf bound_ctrl:1
	v_pk_fma_f32 v[242:243], v[146:147], v[234:235], v[242:243] op_sel_hi:[0,1,1] neg_lo:[1,0,0] neg_hi:[1,0,0]
	v_pk_fma_f32 v[244:245], v[146:147], v[236:237], v[244:245] op_sel_hi:[0,1,1] neg_lo:[1,0,0] neg_hi:[1,0,0]
	v_pk_fma_f32 v[138:139], v[138:139], v[238:239], v[242:243]
	v_pk_fma_f32 v[140:141], v[140:141], v[240:241], v[244:245]
	v_pk_mul_f32 v[144:145], v[138:139], v[164:165]
	v_pk_fma_f32 v[144:145], v[140:141], v[166:167], v[144:145]
	v_add_f32 v146, v144, v145
	ds_read_b128 v[208:211], v10 offset:46080
	ds_read_b128 v[212:215], v10 offset:46336
	ds_read_b128 v[216:219], v10 offset:46592
	ds_read_b128 v[220:223], v10 offset:46848
	ds_read_b128 v[224:227], v10 offset:47104
	ds_read_b32 v228, v11 offset:46080
	v_add_f32_dpp v146, v146, v146 quad_perm:[1,0,3,2] row_mask:0xf bank_mask:0xf bound_ctrl:1
	v_pk_mul_f32 v[246:247], v[138:139], v[246:247]
	v_pk_fma_f32 v[246:247], v[140:141], v[248:249], v[246:247]
	v_add_f32_dpp v146, v146, v146 quad_perm:[2,3,0,1] row_mask:0xf bank_mask:0xf bound_ctrl:1
	v_add_f32 v159, v246, v247
	v_pk_mul_f32 v[176:177], v[176:177], v[184:185] op_sel_hi:[1,0]
	v_add_f32_dpp v146, v146, v146 row_half_mirror row_mask:0xf bank_mask:0xf bound_ctrl:1
	v_pk_mul_f32 v[178:179], v[178:179], v[184:185] op_sel_hi:[1,0]
	s_waitcnt lgkmcnt(6)
	v_add_f32_dpp v146, v146, v146 row_mirror row_mask:0xf bank_mask:0xf bound_ctrl:1
	v_pk_fma_f32 v[176:177], v[146:147], v[168:169], v[176:177] op_sel_hi:[0,1,1] neg_lo:[1,0,0] neg_hi:[1,0,0]
	v_pk_fma_f32 v[178:179], v[146:147], v[170:171], v[178:179] op_sel_hi:[0,1,1] neg_lo:[1,0,0] neg_hi:[1,0,0]
	v_pk_fma_f32 v[138:139], v[138:139], v[172:173], v[176:177]
	v_pk_fma_f32 v[140:141], v[140:141], v[174:175], v[178:179]
	v_pk_mul_f32 v[144:145], v[138:139], v[186:187]
	v_pk_fma_f32 v[144:145], v[140:141], v[188:189], v[144:145]
	v_add_f32 v146, v144, v145
	ds_read_b128 v[230:233], v10 offset:47616
	ds_read_b128 v[234:237], v10 offset:47872
	ds_read_b128 v[238:241], v10 offset:48128
	ds_read_b128 v[242:245], v10 offset:48384
	ds_read_b128 v[246:249], v10 offset:48640
	ds_read_b32 v250, v11 offset:47616
	v_add_f32_dpp v146, v146, v146 quad_perm:[1,0,3,2] row_mask:0xf bank_mask:0xf bound_ctrl:1
	v_pk_mul_f32 v[180:181], v[138:139], v[180:181]
	v_pk_fma_f32 v[180:181], v[140:141], v[182:183], v[180:181]
	v_add_f32_dpp v146, v146, v146 quad_perm:[2,3,0,1] row_mask:0xf bank_mask:0xf bound_ctrl:1
	v_add_f32 v160, v180, v181
	v_pk_mul_f32 v[198:199], v[198:199], v[206:207] op_sel_hi:[1,0]
	v_add_f32_dpp v146, v146, v146 row_half_mirror row_mask:0xf bank_mask:0xf bound_ctrl:1
	v_pk_mul_f32 v[200:201], v[200:201], v[206:207] op_sel_hi:[1,0]
	s_waitcnt lgkmcnt(6)
	v_add_f32_dpp v146, v146, v146 row_mirror row_mask:0xf bank_mask:0xf bound_ctrl:1
	v_pk_fma_f32 v[198:199], v[146:147], v[190:191], v[198:199] op_sel_hi:[0,1,1] neg_lo:[1,0,0] neg_hi:[1,0,0]
	v_pk_fma_f32 v[200:201], v[146:147], v[192:193], v[200:201] op_sel_hi:[0,1,1] neg_lo:[1,0,0] neg_hi:[1,0,0]
	v_pk_fma_f32 v[138:139], v[138:139], v[194:195], v[198:199]
	v_pk_fma_f32 v[140:141], v[140:141], v[196:197], v[200:201]
	v_pk_mul_f32 v[144:145], v[138:139], v[208:209]
	v_pk_fma_f32 v[144:145], v[140:141], v[210:211], v[144:145]
	v_add_f32 v146, v144, v145
	s_nop 1
	v_add_f32_dpp v146, v146, v146 quad_perm:[1,0,3,2] row_mask:0xf bank_mask:0xf bound_ctrl:1
	v_pk_mul_f32 v[202:203], v[138:139], v[202:203]
	v_pk_fma_f32 v[202:203], v[140:141], v[204:205], v[202:203]
	v_add_f32_dpp v146, v146, v146 quad_perm:[2,3,0,1] row_mask:0xf bank_mask:0xf bound_ctrl:1
	v_add_f32 v161, v202, v203
	v_pk_mul_f32 v[220:221], v[220:221], v[228:229] op_sel_hi:[1,0]
	v_add_f32_dpp v146, v146, v146 row_half_mirror row_mask:0xf bank_mask:0xf bound_ctrl:1
	v_pk_mul_f32 v[222:223], v[222:223], v[228:229] op_sel_hi:[1,0]
	s_waitcnt lgkmcnt(0)
	v_add_f32_dpp v146, v146, v146 row_mirror row_mask:0xf bank_mask:0xf bound_ctrl:1
	v_pk_fma_f32 v[220:221], v[146:147], v[212:213], v[220:221] op_sel_hi:[0,1,1] neg_lo:[1,0,0] neg_hi:[1,0,0]
	v_pk_fma_f32 v[222:223], v[146:147], v[214:215], v[222:223] op_sel_hi:[0,1,1] neg_lo:[1,0,0] neg_hi:[1,0,0]
	v_pk_fma_f32 v[138:139], v[138:139], v[216:217], v[220:221]
	v_pk_fma_f32 v[140:141], v[140:141], v[218:219], v[222:223]
	v_pk_mul_f32 v[144:145], v[138:139], v[230:231]
	v_pk_fma_f32 v[144:145], v[140:141], v[232:233], v[144:145]
	v_add_f32 v146, v144, v145
	s_nop 1
	v_add_f32_dpp v146, v146, v146 quad_perm:[1,0,3,2] row_mask:0xf bank_mask:0xf bound_ctrl:1
	v_pk_mul_f32 v[224:225], v[138:139], v[224:225]
	v_pk_fma_f32 v[224:225], v[140:141], v[226:227], v[224:225]
	v_add_f32_dpp v146, v146, v146 quad_perm:[2,3,0,1] row_mask:0xf bank_mask:0xf bound_ctrl:1
	v_add_f32 v162, v224, v225
	v_pk_mul_f32 v[242:243], v[242:243], v[250:251] op_sel_hi:[1,0]
	v_add_f32_dpp v146, v146, v146 row_half_mirror row_mask:0xf bank_mask:0xf bound_ctrl:1
	v_pk_mul_f32 v[244:245], v[244:245], v[250:251] op_sel_hi:[1,0]
	s_nop 0
	v_add_f32_dpp v146, v146, v146 row_mirror row_mask:0xf bank_mask:0xf bound_ctrl:1
	v_pk_fma_f32 v[242:243], v[146:147], v[234:235], v[242:243] op_sel_hi:[0,1,1] neg_lo:[1,0,0] neg_hi:[1,0,0]
	v_pk_fma_f32 v[244:245], v[146:147], v[236:237], v[244:245] op_sel_hi:[0,1,1] neg_lo:[1,0,0] neg_hi:[1,0,0]
	v_pk_fma_f32 v[138:139], v[138:139], v[238:239], v[242:243]
	v_pk_fma_f32 v[140:141], v[140:141], v[240:241], v[244:245]
	v_pk_mul_f32 v[246:247], v[138:139], v[246:247]
	v_pk_fma_f32 v[246:247], v[140:141], v[248:249], v[246:247]
	v_add_f32 v163, v246, v247
	s_nop 0
	v_add_f32_dpp v230, v148, v148 row_mirror row_mask:0xf bank_mask:0x3 bound_ctrl:1
	v_add_f32_dpp v230, v156, v156 row_mirror row_mask:0xf bank_mask:0xc bound_ctrl:1
	v_add_f32_dpp v231, v149, v149 row_mirror row_mask:0xf bank_mask:0x3 bound_ctrl:1
	v_add_f32_dpp v231, v157, v157 row_mirror row_mask:0xf bank_mask:0xc bound_ctrl:1
	v_add_f32_dpp v232, v150, v150 row_mirror row_mask:0xf bank_mask:0x3 bound_ctrl:1
	v_add_f32_dpp v232, v158, v158 row_mirror row_mask:0xf bank_mask:0xc bound_ctrl:1
	v_add_f32_dpp v233, v151, v151 row_mirror row_mask:0xf bank_mask:0x3 bound_ctrl:1
	v_add_f32_dpp v233, v159, v159 row_mirror row_mask:0xf bank_mask:0xc bound_ctrl:1
	v_add_f32_dpp v234, v152, v152 row_mirror row_mask:0xf bank_mask:0x3 bound_ctrl:1
	v_add_f32_dpp v234, v160, v160 row_mirror row_mask:0xf bank_mask:0xc bound_ctrl:1
	v_add_f32_dpp v235, v153, v153 row_mirror row_mask:0xf bank_mask:0x3 bound_ctrl:1
	v_add_f32_dpp v235, v161, v161 row_mirror row_mask:0xf bank_mask:0xc bound_ctrl:1
	v_add_f32_dpp v236, v154, v154 row_mirror row_mask:0xf bank_mask:0x3 bound_ctrl:1
	v_add_f32_dpp v236, v162, v162 row_mirror row_mask:0xf bank_mask:0xc bound_ctrl:1
	v_add_f32_dpp v237, v155, v155 row_mirror row_mask:0xf bank_mask:0x3 bound_ctrl:1
	v_add_f32_dpp v237, v163, v163 row_mirror row_mask:0xf bank_mask:0xc bound_ctrl:1
	v_add_f32_dpp v238, v230, v230 row_half_mirror row_mask:0xf bank_mask:0x5 bound_ctrl:1
	v_add_f32_dpp v238, v234, v234 row_half_mirror row_mask:0xf bank_mask:0xa bound_ctrl:1
	v_add_f32_dpp v239, v231, v231 row_half_mirror row_mask:0xf bank_mask:0x5 bound_ctrl:1
	v_add_f32_dpp v239, v235, v235 row_half_mirror row_mask:0xf bank_mask:0xa bound_ctrl:1
	v_add_f32_dpp v240, v232, v232 row_half_mirror row_mask:0xf bank_mask:0x5 bound_ctrl:1
	v_add_f32_dpp v240, v236, v236 row_half_mirror row_mask:0xf bank_mask:0xa bound_ctrl:1
	v_add_f32_dpp v241, v233, v233 row_half_mirror row_mask:0xf bank_mask:0x5 bound_ctrl:1
	v_add_f32_dpp v241, v237, v237 row_half_mirror row_mask:0xf bank_mask:0xa bound_ctrl:1
	v_and_b32 v244, 2, v3
	v_cmp_ne_u32 vcc, 0, v244
	v_cndmask_b32 v244, v240, v238, vcc
	v_cndmask_b32 v245, v241, v239, vcc
	v_cndmask_b32 v242, v238, v240, vcc
	v_cndmask_b32 v243, v239, v241, vcc
	v_add_f32_dpp v242, v244, v242 quad_perm:[2,3,0,1] row_mask:0xf bank_mask:0xf bound_ctrl:1
	v_add_f32_dpp v243, v245, v243 quad_perm:[2,3,0,1] row_mask:0xf bank_mask:0xf bound_ctrl:1
	v_and_b32 v244, 1, v3
	v_cmp_ne_u32 vcc, 0, v244
	v_cndmask_b32 v244, v243, v242, vcc
	v_cndmask_b32 v245, v242, v243, vcc
	s_nop 0
	v_add_f32_dpp v19, v244, v245 quad_perm:[1,0,3,2] row_mask:0xf bank_mask:0xf bound_ctrl:1
	v_mov_b32 v2, v138
	v_mov_b32 v13, v139
	v_mov_b32 v12, v140
	v_mov_b32 v8, v141

; #define SCAN_BAR() asm volatile("s_barrier" ::: "memory")
; __device__ __forceinline__ void scan_unit(const Ctx& C0, const float* scn, int T, int quarter, const float* S0, float* Sout, unsigned char* obase, int mode) {
;     ...
;             if (mode == 0) { *(float*)(obase + (size_t)(k * 32 + q) * UPITCH_B + rl * 4) = osel0; *(float*)(obase + (size_t)(k * 32 + 16 + q) * UPITCH_B + rl * 4) = osel1; }
;             SCAN_BAR();
;         }
;         if (mode == 0) *(f32x4*)(Sout + irow * 64 + 4 * q) = (f32x4){S0x, S1x, S2x, S3x};
	s_addc_u32 s1, s1, 0
	v_add_co_u32_e32 v16, vcc, s8, v14
	s_cmp_lg_u32 s0, 0x5600000
	s_nop 0
	v_addc_co_u32_e32 v17, vcc, 0, v15, vcc
	v_add_co_u32_e32 v14, vcc, 0xfcaa000, v14
	global_store_dword v[16:17], v18, off offset:768
	s_nop 0
	v_addc_co_u32_e32 v15, vcc, 0, v15, vcc
	global_store_dword v[14:15], v19, off offset:768
	s_barrier
	s_cbranch_scc1 .LBB0_685
	v_readlane_b32 s0, v255, 46
	s_add_i32 s0, s3, s0
	s_ashr_i32 s1, s0, 31
	s_lshl_b64 s[0:1], s[0:1], 17
	v_readlane_b32 s3, v253, 26
	s_add_u32 s0, s3, s0
	v_readlane_b32 s3, v253, 27
	s_addc_u32 s1, s3, s1
	s_lshl_b32 s2, s2, 14
	s_add_u32 s0, s0, s2
	s_addc_u32 s1, s1, 0
	v_lshlrev_b32_e32 v0, 8, v0
	v_lshl_add_u64 v[6:7], s[0:1], 0, v[0:1]
	v_mov_b32_e32 v5, v1
	v_lshl_add_u64 v[6:7], v[6:7], 0, v[4:5]
	v_mov_b32_e32 v3, v13
	v_mov_b32_e32 v4, v12
	v_mov_b32_e32 v5, v8
	global_store_dwordx4 v[6:7], v[2:5], off
